# P2/P4/P7: wave halves stay staggered across unit boundaries (no pre/post-epilogue align barriers except before the last unit); with barrier edits + P2 plain stores
# baseline (speedup 1.0000x reference)
;     __device__ bool next(int i, pg8::Unit& u) const { const int L = i * cph + k; if (L >= nunits) return false; const int nig = 8 * nN, gid = L / nig, w = L % nig; u.pm = 16 * xh + 8 * gid + (w & 7); u.pn = w >> 3; return true; }
; template <class Epi, class Sched, bool ALIGN_EPI = false, bool SP2 = false>
; __device__ __forceinline__ void gemm_phase(PG8_LAS unsigned char* lds, const Gemm g, const Sched& S, const Epi& E, volatile PG8_LAS unsigned* sw = nullptr) {
;     ...
;         const bool has_next = S.next(ui + 1, nxt);
;         const char* nA = has_next ? (const char*)g.A + (size_t)nxt.pm * tstep : cA; const char* nB = has_next ? (const char*)g.Bt + (size_t)nxt.pn * tstep : cB;
.LBB0_159:
	s_add_i32 s43, s43, 1
	s_mul_i32 s3, s43, s62
	s_add_i32 s3, s3, s97
	s_cmpk_lt_i32 s3, 0x80
	s_cselect_b64 s[28:29], -1, 0
	s_cselect_b32 s98, 1, 0
	s_cmpk_gt_i32 s3, 0x7f
	s_cbranch_scc1 .LBB0_161
	s_ashr_i32 s10, s3, 31
	s_lshr_b32 s10, s10, 26
	s_add_i32 s10, s3, s10
	s_ashr_i32 s11, s10, 6
	s_andn2_b32 s10, s10, 63
	s_sub_i32 s3, s3, s10
	s_lshl_b32 s10, s11, 3
	s_add_i32 s10, s10, s60
	s_and_b32 s11, s3, 7
	s_or_b32 s10, s10, s11
	s_ashr_i32 s12, s3, 3

; #define PG8_STAGE(bufoff, gbase, voff) do { _Pragma("unroll") for (int _i = 0; _i < 2; ++_i) \
;         __builtin_amdgcn_global_load_lds((const unsigned*)((const char*)(gbase) + (voff)[_i]), (PG8_LAS unsigned*)(lds + (bufoff) + ldsw + _i * 8192), 16, 0, 0); } while (0)
; #define PG8_LDA(dst, b, h) do { _Pragma("unroll") for (int m = 0; m < 4; ++m) _Pragma("unroll") for (int k = 0; k < 2; ++k) dst[m][k] = *(const PG8_LAS bf16x8*)(lds + PG8_SA(b, h) + aoff + m * 2048 + k * 1024); } while (0)
; #define PG8_LDB(dst, b, h) do { _Pragma("unroll") for (int n = 0; n < 2; ++n) _Pragma("unroll") for (int k = 0; k < 2; ++k) dst[n][k] = *(const PG8_LAS bf16x8*)(lds + PG8_SB(b, h) + boff + n * 2048 + k * 1024); } while (0)
; #define PG8_MMA(ai, bj, At, Bt) do { __builtin_amdgcn_s_setprio(1); _Pragma("unroll") for (int m = 0; m < 4; ++m) _Pragma("unroll") for (int n = 0; n < 2; ++n) _Pragma("unroll") for (int k = 0; k < 2; ++k) \
;         acc[ai][bj][m][n] = __builtin_amdgcn_mfma_f32_16x16x32_bf16(Bt[n][k], At[m][k], acc[ai][bj][m][n], 0, 0, 0); __builtin_amdgcn_s_setprio(0); } while (0)
; #define PG8_WAIT_V(n) asm volatile("s_waitcnt vmcnt(" #n ")" ::: "memory")
; #define PG8_WAIT_L(n) asm volatile("s_waitcnt lgkmcnt(" #n ")" ::: "memory")
; #define PG8_BAR __builtin_amdgcn_s_barrier()
; #define PG8_SCHED __builtin_amdgcn_sched_barrier(0)
; template <class Epi, class Sched, bool ALIGN_EPI = false, bool SP2 = false>
; __device__ __forceinline__ void gemm_phase(PG8_LAS unsigned char* lds, const Gemm g, const Sched& S, const Epi& E, volatile PG8_LAS unsigned* sw = nullptr) {
;     ...
;             PG8_LDB(B0, 0, 0); PG8_LDB(B1, 0, 1); PG8_SCHED; PG8_LDA(At, 0, 0); PG8_STAGE(PG8_SA(1, 1), a1 + hstep, voffA);
;             PG8_WAIT_V(8); PG8_WAIT_L(0); PG8_BAR; PG8_MMA(0, 0, At, B0); PG8_MMA(0, 1, At, B1); PG8_BAR; PG8_SCHED;
;             PG8_LDA(At, 0, 1); PG8_STAGE(PG8_SB(0, 0), b2, voffB); PG8_STAGE(PG8_SB(0, 1), b2 + hstep, voffB); PG8_STAGE(PG8_SA(0, 0), a2, voffA);
;             PG8_WAIT_V(8); PG8_WAIT_L(0); PG8_BAR; PG8_MMA(1, 0, At, B0); PG8_MMA(1, 1, At, B1); PG8_BAR; PG8_SCHED;
.LBB0_162:
	ds_read_b128 v[150:153], v146
	ds_read_b128 v[154:157], v146 offset:1024
	ds_read_b128 v[158:161], v146 offset:2048
	ds_read_b128 v[162:165], v146 offset:3072
	ds_read_b128 v[166:169], v147
	ds_read_b128 v[170:173], v147 offset:1024
	ds_read_b128 v[174:177], v147 offset:2048
	ds_read_b128 v[178:181], v147 offset:3072
	s_add_u32 s50, s48, 0x4000
	s_addc_u32 s51, s49, 0
	s_cmp_eq_u32 s65, 12
	s_cselect_b32 s54, s11, s50
	s_cselect_b32 s55, s3, s51
	s_cselect_b32 s52, s47, s59
	s_cselect_b32 s53, s13, s64
	s_add_u32 s50, s54, 0x8000
	s_addc_u32 s51, s55, 0
	v_lshl_add_u64 v[142:143], s[48:49], 0, v[138:139]
	s_add_i32 m0, s20, 0xc000
	ds_read_b128 v[182:185], v148
	ds_read_b128 v[186:189], v148 offset:1024
	ds_read_b128 v[190:193], v148 offset:2048
	ds_read_b128 v[194:197], v148 offset:3072
	ds_read_b128 v[198:201], v148 offset:4096
	ds_read_b128 v[202:205], v148 offset:5120
	ds_read_b128 v[206:209], v148 offset:6144
	ds_read_b128 v[210:213], v148 offset:7168
	global_load_lds_dwordx4 v[142:143], off
	v_lshl_add_u64 v[142:143], s[48:49], 0, v[140:141]
	s_add_i32 m0, s20, 0xe000
	s_nop 0
	global_load_lds_dwordx4 v[142:143], off
	s_waitcnt vmcnt(8)
	s_waitcnt lgkmcnt(0)
	s_barrier
	s_setprio 1
	s_waitcnt lgkmcnt(0)
	v_mfma_f32_16x16x32_bf16 v[126:129], v[150:153], v[182:185], v[126:129]
	v_mfma_f32_16x16x32_bf16 v[122:125], v[158:161], v[182:185], v[122:125]
	v_mfma_f32_16x16x32_bf16 v[118:121], v[150:153], v[190:193], v[118:121]
	v_mfma_f32_16x16x32_bf16 v[110:113], v[158:161], v[190:193], v[110:113]
	v_mfma_f32_16x16x32_bf16 v[102:105], v[150:153], v[198:201], v[102:105]
	v_mfma_f32_16x16x32_bf16 v[94:97], v[158:161], v[198:201], v[94:97]
	v_mfma_f32_16x16x32_bf16 v[86:89], v[150:153], v[206:209], v[86:89]
	v_mfma_f32_16x16x32_bf16 v[78:81], v[158:161], v[206:209], v[78:81]
	v_mfma_f32_16x16x32_bf16 v[126:129], v[154:157], v[186:189], v[126:129]
	v_mfma_f32_16x16x32_bf16 v[122:125], v[162:165], v[186:189], v[122:125]
	v_mfma_f32_16x16x32_bf16 v[118:121], v[154:157], v[194:197], v[118:121]
	v_mfma_f32_16x16x32_bf16 v[110:113], v[162:165], v[194:197], v[110:113]
	v_mfma_f32_16x16x32_bf16 v[102:105], v[154:157], v[202:205], v[102:105]
	v_mfma_f32_16x16x32_bf16 v[94:97], v[162:165], v[202:205], v[94:97]
	v_mfma_f32_16x16x32_bf16 v[86:89], v[154:157], v[210:213], v[86:89]
	v_mfma_f32_16x16x32_bf16 v[78:81], v[162:165], v[210:213], v[78:81]
	s_setprio 0
	s_setprio 1
	v_mfma_f32_16x16x32_bf16 v[114:117], v[166:169], v[182:185], v[114:117]
	v_mfma_f32_16x16x32_bf16 v[106:109], v[174:177], v[182:185], v[106:109]
	v_mfma_f32_16x16x32_bf16 v[98:101], v[166:169], v[190:193], v[98:101]
	v_mfma_f32_16x16x32_bf16 v[90:93], v[174:177], v[190:193], v[90:93]
	v_mfma_f32_16x16x32_bf16 v[82:85], v[166:169], v[198:201], v[82:85]
	v_mfma_f32_16x16x32_bf16 v[74:77], v[174:177], v[198:201], v[74:77]
	v_mfma_f32_16x16x32_bf16 v[70:73], v[166:169], v[206:209], v[70:73]
	v_mfma_f32_16x16x32_bf16 v[66:69], v[174:177], v[206:209], v[66:69]
	v_mfma_f32_16x16x32_bf16 v[114:117], v[170:173], v[186:189], v[114:117]
	v_mfma_f32_16x16x32_bf16 v[106:109], v[178:181], v[186:189], v[106:109]
	v_mfma_f32_16x16x32_bf16 v[98:101], v[170:173], v[194:197], v[98:101]
	v_mfma_f32_16x16x32_bf16 v[90:93], v[178:181], v[194:197], v[90:93]
	v_mfma_f32_16x16x32_bf16 v[82:85], v[170:173], v[202:205], v[82:85]
	v_mfma_f32_16x16x32_bf16 v[74:77], v[178:181], v[202:205], v[74:77]
	v_mfma_f32_16x16x32_bf16 v[70:73], v[170:173], v[210:213], v[70:73]
	v_mfma_f32_16x16x32_bf16 v[66:69], v[178:181], v[210:213], v[66:69]
	s_setprio 0
	s_barrier
	s_add_i32 s70, s57, s19
	v_lshl_add_u64 v[142:143], s[52:53], 0, v[134:135]
	s_mov_b32 m0, s70
	ds_read_b128 v[182:185], v148 offset:16384
	ds_read_b128 v[186:189], v148 offset:17408
	ds_read_b128 v[190:193], v148 offset:18432
	ds_read_b128 v[194:197], v148 offset:19456
	ds_read_b128 v[198:201], v148 offset:20480
	ds_read_b128 v[202:205], v148 offset:21504
	ds_read_b128 v[206:209], v148 offset:22528
	ds_read_b128 v[210:213], v148 offset:23552
	global_load_lds_dwordx4 v[142:143], off
	s_add_i32 m0, s70, 0x2000
	s_add_u32 s70, s52, 0x4000
	v_lshl_add_u64 v[142:143], s[52:53], 0, v[130:131]
	s_addc_u32 s71, s53, 0
	s_add_i32 s72, s58, s19
	global_load_lds_dwordx4 v[142:143], off
	v_lshl_add_u64 v[142:143], s[70:71], 0, v[134:135]
	s_mov_b32 m0, s72
	s_nop 0
	global_load_lds_dwordx4 v[142:143], off
	v_lshl_add_u64 v[142:143], s[70:71], 0, v[130:131]
	s_add_i32 m0, s72, 0x2000
	s_nop 0
	global_load_lds_dwordx4 v[142:143], off
	v_lshl_add_u64 v[142:143], s[54:55], 0, v[136:137]
	s_mov_b32 m0, s20
	s_nop 0
	global_load_lds_dwordx4 v[142:143], off
	v_lshl_add_u64 v[142:143], s[54:55], 0, v[132:133]
	s_mov_b32 m0, s21
	s_nop 0
	global_load_lds_dwordx4 v[142:143], off
	s_waitcnt vmcnt(8)
	s_waitcnt lgkmcnt(0)
	s_barrier
; #define PG8_STAGE(bufoff, gbase, voff) do { _Pragma("unroll") for (int _i = 0; _i < 2; ++_i) \
;         __builtin_amdgcn_global_load_lds((const unsigned*)((const char*)(gbase) + (voff)[_i]), (PG8_LAS unsigned*)(lds + (bufoff) + ldsw + _i * 8192), 16, 0, 0); } while (0)
; #define PG8_LDA(dst, b, h) do { _Pragma("unroll") for (int m = 0; m < 4; ++m) _Pragma("unroll") for (int k = 0; k < 2; ++k) dst[m][k] = *(const PG8_LAS bf16x8*)(lds + PG8_SA(b, h) + aoff + m * 2048 + k * 1024); } while (0)
; #define PG8_LDB(dst, b, h) do { _Pragma("unroll") for (int n = 0; n < 2; ++n) _Pragma("unroll") for (int k = 0; k < 2; ++k) dst[n][k] = *(const PG8_LAS bf16x8*)(lds + PG8_SB(b, h) + boff + n * 2048 + k * 1024); } while (0)
; #define PG8_MMA(ai, bj, At, Bt) do { __builtin_amdgcn_s_setprio(1); _Pragma("unroll") for (int m = 0; m < 4; ++m) _Pragma("unroll") for (int n = 0; n < 2; ++n) _Pragma("unroll") for (int k = 0; k < 2; ++k) \
;         acc[ai][bj][m][n] = __builtin_amdgcn_mfma_f32_16x16x32_bf16(Bt[n][k], At[m][k], acc[ai][bj][m][n], 0, 0, 0); __builtin_amdgcn_s_setprio(0); } while (0)
; #define PG8_WAIT_V(n) asm volatile("s_waitcnt vmcnt(" #n ")" ::: "memory")
; #define PG8_WAIT_L(n) asm volatile("s_waitcnt lgkmcnt(" #n ")" ::: "memory")
; #define PG8_BAR __builtin_amdgcn_s_barrier()
; #define PG8_SCHED __builtin_amdgcn_sched_barrier(0)
; template <class Epi, class Sched, bool ALIGN_EPI = false, bool SP2 = false>
; __device__ __forceinline__ void gemm_phase(PG8_LAS unsigned char* lds, const Gemm g, const Sched& S, const Epi& E, volatile PG8_LAS unsigned* sw = nullptr) {
;     ...
;             PG8_WAIT_V(8); PG8_WAIT_L(0); PG8_BAR; PG8_MMA(1, 0, At, B0); PG8_MMA(1, 1, At, B1); PG8_BAR; PG8_SCHED;
;             PG8_LDB(B0, 1, 0); PG8_LDB(B1, 1, 1); PG8_SCHED; PG8_LDA(At, 1, 0); PG8_STAGE(PG8_SA(0, 1), a2 + hstep, voffA);
;             PG8_WAIT_V(8); PG8_WAIT_L(0); PG8_BAR; PG8_MMA(0, 0, At, B0); PG8_MMA(0, 1, At, B1); PG8_BAR; PG8_SCHED;
	s_setprio 1
	s_waitcnt lgkmcnt(0)
	v_mfma_f32_16x16x32_bf16 v[62:65], v[150:153], v[182:185], v[62:65]
	v_mfma_f32_16x16x32_bf16 v[58:61], v[158:161], v[182:185], v[58:61]
	v_mfma_f32_16x16x32_bf16 v[54:57], v[150:153], v[190:193], v[54:57]
	v_mfma_f32_16x16x32_bf16 v[46:49], v[158:161], v[190:193], v[46:49]
	v_mfma_f32_16x16x32_bf16 v[38:41], v[150:153], v[198:201], v[38:41]
	v_mfma_f32_16x16x32_bf16 v[30:33], v[158:161], v[198:201], v[30:33]
	v_mfma_f32_16x16x32_bf16 v[22:25], v[150:153], v[206:209], v[22:25]
	v_mfma_f32_16x16x32_bf16 v[14:17], v[158:161], v[206:209], v[14:17]
	v_mfma_f32_16x16x32_bf16 v[62:65], v[154:157], v[186:189], v[62:65]
	v_mfma_f32_16x16x32_bf16 v[58:61], v[162:165], v[186:189], v[58:61]
	v_mfma_f32_16x16x32_bf16 v[54:57], v[154:157], v[194:197], v[54:57]
	v_mfma_f32_16x16x32_bf16 v[46:49], v[162:165], v[194:197], v[46:49]
	v_mfma_f32_16x16x32_bf16 v[38:41], v[154:157], v[202:205], v[38:41]
	v_mfma_f32_16x16x32_bf16 v[30:33], v[162:165], v[202:205], v[30:33]
	v_mfma_f32_16x16x32_bf16 v[22:25], v[154:157], v[210:213], v[22:25]
	v_mfma_f32_16x16x32_bf16 v[14:17], v[162:165], v[210:213], v[14:17]
	s_setprio 0
	s_setprio 1
	v_mfma_f32_16x16x32_bf16 v[50:53], v[166:169], v[182:185], v[50:53]
	v_mfma_f32_16x16x32_bf16 v[42:45], v[174:177], v[182:185], v[42:45]
	v_mfma_f32_16x16x32_bf16 v[34:37], v[166:169], v[190:193], v[34:37]
	v_mfma_f32_16x16x32_bf16 v[26:29], v[174:177], v[190:193], v[26:29]
	v_mfma_f32_16x16x32_bf16 v[18:21], v[166:169], v[198:201], v[18:21]
	v_mfma_f32_16x16x32_bf16 v[10:13], v[174:177], v[198:201], v[10:13]
	v_mfma_f32_16x16x32_bf16 v[6:9], v[166:169], v[206:209], v[6:9]
	v_mfma_f32_16x16x32_bf16 v[2:5], v[174:177], v[206:209], v[2:5]
	v_mfma_f32_16x16x32_bf16 v[50:53], v[170:173], v[186:189], v[50:53]
	v_mfma_f32_16x16x32_bf16 v[42:45], v[178:181], v[186:189], v[42:45]
	v_mfma_f32_16x16x32_bf16 v[34:37], v[170:173], v[194:197], v[34:37]
	v_mfma_f32_16x16x32_bf16 v[26:29], v[178:181], v[194:197], v[26:29]
	v_mfma_f32_16x16x32_bf16 v[18:21], v[170:173], v[202:205], v[18:21]
	v_mfma_f32_16x16x32_bf16 v[10:13], v[178:181], v[202:205], v[10:13]
	v_mfma_f32_16x16x32_bf16 v[6:9], v[170:173], v[210:213], v[6:9]
	v_mfma_f32_16x16x32_bf16 v[2:5], v[178:181], v[210:213], v[2:5]
	s_setprio 0
	s_barrier
	s_add_i32 s70, 0, 0x18000
	v_add_u32_e32 v142, s70, v144
	s_add_i32 s71, 0, 0x1c000
	ds_read_b128 v[150:153], v142
	ds_read_b128 v[154:157], v142 offset:1024
	ds_read_b128 v[158:161], v142 offset:2048
	ds_read_b128 v[162:165], v142 offset:3072
	v_add_u32_e32 v142, s71, v144
	ds_read_b128 v[166:169], v142
	ds_read_b128 v[170:173], v142 offset:1024
	ds_read_b128 v[174:177], v142 offset:2048
	ds_read_b128 v[178:181], v142 offset:3072
	s_add_u32 s54, s54, 0x4000
	s_addc_u32 s55, s55, 0
	s_mov_b32 m0, s22
	v_lshl_add_u64 v[142:143], s[54:55], 0, v[136:137]
	ds_read_b128 v[182:185], v148 offset:32768
	ds_read_b128 v[186:189], v148 offset:33792
	ds_read_b128 v[190:193], v148 offset:34816
	ds_read_b128 v[194:197], v148 offset:35840
	ds_read_b128 v[198:201], v148 offset:36864
	ds_read_b128 v[202:205], v148 offset:37888
	ds_read_b128 v[206:209], v148 offset:38912
	ds_read_b128 v[210:213], v148 offset:39936
	global_load_lds_dwordx4 v[142:143], off
	v_lshl_add_u64 v[142:143], s[54:55], 0, v[132:133]
	s_mov_b32 m0, s23
	s_nop 0
	global_load_lds_dwordx4 v[142:143], off
	s_waitcnt vmcnt(8)
	s_waitcnt lgkmcnt(0)
	s_barrier
	s_setprio 1
	s_waitcnt lgkmcnt(0)
	v_mfma_f32_16x16x32_bf16 v[126:129], v[150:153], v[182:185], v[126:129]
	v_mfma_f32_16x16x32_bf16 v[122:125], v[158:161], v[182:185], v[122:125]
	v_mfma_f32_16x16x32_bf16 v[118:121], v[150:153], v[190:193], v[118:121]
	v_mfma_f32_16x16x32_bf16 v[110:113], v[158:161], v[190:193], v[110:113]
	v_mfma_f32_16x16x32_bf16 v[102:105], v[150:153], v[198:201], v[102:105]
	v_mfma_f32_16x16x32_bf16 v[94:97], v[158:161], v[198:201], v[94:97]
	v_mfma_f32_16x16x32_bf16 v[86:89], v[150:153], v[206:209], v[86:89]
	v_mfma_f32_16x16x32_bf16 v[78:81], v[158:161], v[206:209], v[78:81]
	v_mfma_f32_16x16x32_bf16 v[126:129], v[154:157], v[186:189], v[126:129]
	v_mfma_f32_16x16x32_bf16 v[122:125], v[162:165], v[186:189], v[122:125]
	v_mfma_f32_16x16x32_bf16 v[118:121], v[154:157], v[194:197], v[118:121]
	v_mfma_f32_16x16x32_bf16 v[110:113], v[162:165], v[194:197], v[110:113]
	v_mfma_f32_16x16x32_bf16 v[102:105], v[154:157], v[202:205], v[102:105]
	v_mfma_f32_16x16x32_bf16 v[94:97], v[162:165], v[202:205], v[94:97]
	v_mfma_f32_16x16x32_bf16 v[86:89], v[154:157], v[210:213], v[86:89]
	v_mfma_f32_16x16x32_bf16 v[78:81], v[162:165], v[210:213], v[78:81]
	s_setprio 0
	s_setprio 1
	v_mfma_f32_16x16x32_bf16 v[114:117], v[166:169], v[182:185], v[114:117]
	v_mfma_f32_16x16x32_bf16 v[106:109], v[174:177], v[182:185], v[106:109]
	v_mfma_f32_16x16x32_bf16 v[98:101], v[166:169], v[190:193], v[98:101]
	v_mfma_f32_16x16x32_bf16 v[90:93], v[174:177], v[190:193], v[90:93]
	v_mfma_f32_16x16x32_bf16 v[82:85], v[166:169], v[198:201], v[82:85]
	v_mfma_f32_16x16x32_bf16 v[74:77], v[174:177], v[198:201], v[74:77]
	v_mfma_f32_16x16x32_bf16 v[70:73], v[166:169], v[206:209], v[70:73]
	v_mfma_f32_16x16x32_bf16 v[66:69], v[174:177], v[206:209], v[66:69]
	v_mfma_f32_16x16x32_bf16 v[114:117], v[170:173], v[186:189], v[114:117]
	v_mfma_f32_16x16x32_bf16 v[106:109], v[178:181], v[186:189], v[106:109]
	v_mfma_f32_16x16x32_bf16 v[98:101], v[170:173], v[194:197], v[98:101]
	v_mfma_f32_16x16x32_bf16 v[90:93], v[178:181], v[194:197], v[90:93]
	v_mfma_f32_16x16x32_bf16 v[82:85], v[170:173], v[202:205], v[82:85]
	v_mfma_f32_16x16x32_bf16 v[74:77], v[178:181], v[202:205], v[74:77]
	v_mfma_f32_16x16x32_bf16 v[70:73], v[170:173], v[210:213], v[70:73]
	v_mfma_f32_16x16x32_bf16 v[66:69], v[178:181], v[210:213], v[66:69]
	s_setprio 0
	s_barrier
; #define PG8_STAGE(bufoff, gbase, voff) do { _Pragma("unroll") for (int _i = 0; _i < 2; ++_i) \
;         __builtin_amdgcn_global_load_lds((const unsigned*)((const char*)(gbase) + (voff)[_i]), (PG8_LAS unsigned*)(lds + (bufoff) + ldsw + _i * 8192), 16, 0, 0); } while (0)
; #define PG8_LDA(dst, b, h) do { _Pragma("unroll") for (int m = 0; m < 4; ++m) _Pragma("unroll") for (int k = 0; k < 2; ++k) dst[m][k] = *(const PG8_LAS bf16x8*)(lds + PG8_SA(b, h) + aoff + m * 2048 + k * 1024); } while (0)
; #define PG8_MMA(ai, bj, At, Bt) do { __builtin_amdgcn_s_setprio(1); _Pragma("unroll") for (int m = 0; m < 4; ++m) _Pragma("unroll") for (int n = 0; n < 2; ++n) _Pragma("unroll") for (int k = 0; k < 2; ++k) \
;         acc[ai][bj][m][n] = __builtin_amdgcn_mfma_f32_16x16x32_bf16(Bt[n][k], At[m][k], acc[ai][bj][m][n], 0, 0, 0); __builtin_amdgcn_s_setprio(0); } while (0)
; #define PG8_WAIT_V(n) asm volatile("s_waitcnt vmcnt(" #n ")" ::: "memory")
; #define PG8_WAIT_L(n) asm volatile("s_waitcnt lgkmcnt(" #n ")" ::: "memory")
; #define PG8_BAR __builtin_amdgcn_s_barrier()
; #define PG8_SCHED __builtin_amdgcn_sched_barrier(0)
; template <class Epi, class Sched, bool ALIGN_EPI = false, bool SP2 = false>
; __device__ __forceinline__ void gemm_phase(PG8_LAS unsigned char* lds, const Gemm g, const Sched& S, const Epi& E, volatile PG8_LAS unsigned* sw = nullptr) {
;     ...
;             PG8_LDA(At, 1, 1); PG8_STAGE(PG8_SB(1, 0), b3, voffB); PG8_STAGE(PG8_SB(1, 1), b3 + hstep, voffB); PG8_STAGE(PG8_SA(1, 0), a3, voffA);
;             PG8_WAIT_V(8); PG8_WAIT_L(0); PG8_BAR; PG8_MMA(1, 0, At, B0); PG8_MMA(1, 1, At, B1); PG8_BAR; PG8_SCHED;
;     ...
;         if constexpr (ALIGN_EPI) { if (wr == 0) PG8_BAR; }
	s_add_u32 s54, s52, 0x8000
	s_addc_u32 s55, s53, 0
	s_add_i32 s70, s70, s19
	v_lshl_add_u64 v[142:143], s[54:55], 0, v[134:135]
	s_mov_b32 m0, s70
	ds_read_b128 v[182:185], v148 offset:49152
	ds_read_b128 v[186:189], v148 offset:50176
	ds_read_b128 v[190:193], v148 offset:51200
	ds_read_b128 v[194:197], v148 offset:52224
	ds_read_b128 v[198:201], v148 offset:53248
	ds_read_b128 v[202:205], v148 offset:54272
	ds_read_b128 v[206:209], v148 offset:55296
	ds_read_b128 v[210:213], v148 offset:56320
	global_load_lds_dwordx4 v[142:143], off
	s_add_i32 m0, s70, 0x2000
	s_add_u32 s52, s52, 0xc000
	v_lshl_add_u64 v[142:143], s[54:55], 0, v[130:131]
	s_addc_u32 s53, s53, 0
	s_add_i32 s54, s71, s19
	global_load_lds_dwordx4 v[142:143], off
	v_lshl_add_u64 v[142:143], s[52:53], 0, v[134:135]
	s_mov_b32 m0, s54
	s_nop 0
	global_load_lds_dwordx4 v[142:143], off
	v_lshl_add_u64 v[142:143], s[52:53], 0, v[130:131]
	s_add_i32 m0, s54, 0x2000
	s_nop 0
	global_load_lds_dwordx4 v[142:143], off
	v_lshl_add_u64 v[142:143], s[50:51], 0, v[136:137]
	s_mov_b32 m0, s41
	s_nop 0
	global_load_lds_dwordx4 v[142:143], off
	v_lshl_add_u64 v[142:143], s[50:51], 0, v[132:133]
	s_mov_b32 m0, s42
	s_nop 0
	global_load_lds_dwordx4 v[142:143], off
	s_waitcnt vmcnt(8)
	s_waitcnt lgkmcnt(0)
	s_barrier
	s_setprio 1
	s_waitcnt lgkmcnt(0)
	v_mfma_f32_16x16x32_bf16 v[62:65], v[150:153], v[182:185], v[62:65]
	v_mfma_f32_16x16x32_bf16 v[58:61], v[158:161], v[182:185], v[58:61]
	v_mfma_f32_16x16x32_bf16 v[54:57], v[150:153], v[190:193], v[54:57]
	v_mfma_f32_16x16x32_bf16 v[46:49], v[158:161], v[190:193], v[46:49]
	v_mfma_f32_16x16x32_bf16 v[38:41], v[150:153], v[198:201], v[38:41]
	v_mfma_f32_16x16x32_bf16 v[30:33], v[158:161], v[198:201], v[30:33]
	v_mfma_f32_16x16x32_bf16 v[22:25], v[150:153], v[206:209], v[22:25]
	v_mfma_f32_16x16x32_bf16 v[14:17], v[158:161], v[206:209], v[14:17]
	v_mfma_f32_16x16x32_bf16 v[62:65], v[154:157], v[186:189], v[62:65]
	v_mfma_f32_16x16x32_bf16 v[58:61], v[162:165], v[186:189], v[58:61]
	v_mfma_f32_16x16x32_bf16 v[54:57], v[154:157], v[194:197], v[54:57]
	v_mfma_f32_16x16x32_bf16 v[46:49], v[162:165], v[194:197], v[46:49]
	v_mfma_f32_16x16x32_bf16 v[38:41], v[154:157], v[202:205], v[38:41]
	v_mfma_f32_16x16x32_bf16 v[30:33], v[162:165], v[202:205], v[30:33]
	v_mfma_f32_16x16x32_bf16 v[22:25], v[154:157], v[210:213], v[22:25]
	v_mfma_f32_16x16x32_bf16 v[14:17], v[162:165], v[210:213], v[14:17]
	s_setprio 0
	s_setprio 1
	v_mfma_f32_16x16x32_bf16 v[50:53], v[166:169], v[182:185], v[50:53]
	v_mfma_f32_16x16x32_bf16 v[42:45], v[174:177], v[182:185], v[42:45]
	v_mfma_f32_16x16x32_bf16 v[34:37], v[166:169], v[190:193], v[34:37]
	v_mfma_f32_16x16x32_bf16 v[26:29], v[174:177], v[190:193], v[26:29]
	v_mfma_f32_16x16x32_bf16 v[18:21], v[166:169], v[198:201], v[18:21]
	v_mfma_f32_16x16x32_bf16 v[10:13], v[174:177], v[198:201], v[10:13]
	v_mfma_f32_16x16x32_bf16 v[6:9], v[166:169], v[206:209], v[6:9]
	v_mfma_f32_16x16x32_bf16 v[2:5], v[174:177], v[206:209], v[2:5]
	v_mfma_f32_16x16x32_bf16 v[50:53], v[170:173], v[186:189], v[50:53]
	v_mfma_f32_16x16x32_bf16 v[42:45], v[178:181], v[186:189], v[42:45]
	v_mfma_f32_16x16x32_bf16 v[34:37], v[170:173], v[194:197], v[34:37]
	v_mfma_f32_16x16x32_bf16 v[26:29], v[178:181], v[194:197], v[26:29]
	v_mfma_f32_16x16x32_bf16 v[18:21], v[170:173], v[202:205], v[18:21]
	v_mfma_f32_16x16x32_bf16 v[10:13], v[178:181], v[202:205], v[10:13]
	v_mfma_f32_16x16x32_bf16 v[6:9], v[170:173], v[210:213], v[6:9]
	v_mfma_f32_16x16x32_bf16 v[2:5], v[178:181], v[210:213], v[2:5]
	s_setprio 0
	s_barrier
	s_add_i32 s65, s65, 2
	s_add_u32 s48, s48, 0x10000
	s_addc_u32 s49, s49, 0
	s_add_u32 s59, s59, 0x10000
	s_addc_u32 s64, s64, 0
	s_cmp_gt_u32 s65, 13
	s_cbranch_scc0 .LBB0_162
	s_and_b64 vcc, exec, s[6:7]
	s_cbranch_vccz .LBB0_165
	s_cmp_lg_u32 s98, 0
	s_cbranch_scc1 .LBB0_165
	s_barrier

; #define PG8_BAR __builtin_amdgcn_s_barrier()
; template <class Epi, class Sched, bool ALIGN_EPI = false, bool SP2 = false>
; __device__ __forceinline__ void gemm_phase(PG8_LAS unsigned char* lds, const Gemm g, const Sched& S, const Epi& E, volatile PG8_LAS unsigned* sw = nullptr) {
;     ...
;         if (!has_next) break;
; #pragma unroll
;         for (int a = 0; a < 2; ++a)
; #pragma unroll
;             for (int b = 0; b < 2; ++b)
; #pragma unroll
;                 for (int m = 0; m < 4; ++m)
; #pragma unroll
;                     for (int n = 0; n < 2; ++n) acc[a][b][m][n] = (f32x4){0.f, 0.f, 0.f, 0.f};
;         cur = nxt; cA = nA; cB = nB; ++ui;
;         if constexpr (ALIGN_EPI) { if (wr == 1) PG8_BAR; }
.LBB0_169:
	s_andn2_b64 vcc, exec, s[28:29]
	s_mov_b64 s[2:3], -1
	s_cbranch_vccnz .LBB0_158
	s_andn2_b64 vcc, exec, s[4:5]
	s_cbranch_vccnz .LBB0_157
	s_branch .LBB0_157

;     __device__ bool next(int i, pg8::Unit& u) const { const int L = i * cph + k; if (L >= nunits) return false; const int nig = 8 * nN, gid = L / nig, w = L % nig; u.pm = 16 * xh + 8 * gid + (w & 7); u.pn = w >> 3; return true; }
; template <class Epi, class Sched, bool ALIGN_EPI = false, bool SP2 = false>
; __device__ __forceinline__ void gemm_phase(PG8_LAS unsigned char* lds, const Gemm g, const Sched& S, const Epi& E, volatile PG8_LAS unsigned* sw = nullptr) {
;     ...
;         const bool has_next = S.next(ui + 1, nxt);
;         const char* nA = has_next ? (const char*)g.A + (size_t)nxt.pm * tstep : cA; const char* nB = has_next ? (const char*)g.Bt + (size_t)nxt.pn * tstep : cB;
.LBB0_441:
	s_add_i32 s64, s64, 1
	s_mul_i32 s9, s64, s76
	s_add_i32 s9, s9, s97
	s_cmp_lt_i32 s9, 64
	s_cselect_b64 s[26:27], -1, 0
	s_cselect_b32 s98, 1, 0
	s_cmp_gt_i32 s9, 63
	s_cbranch_scc1 .LBB0_443
	s_ashr_i32 s8, s9, 31
	s_lshr_b32 s8, s8, 27
	s_add_i32 s8, s9, s8
	s_ashr_i32 s22, s8, 5
	s_andn2_b32 s8, s8, 31
	s_sub_i32 s9, s9, s8
	s_lshl_b32 s8, s22, 3
	s_add_i32 s8, s8, s77
	s_and_b32 s22, s9, 7
	s_or_b32 s8, s8, s22
	s_ashr_i32 s22, s9, 3

; #define PG8_STAGE(bufoff, gbase, voff) do { _Pragma("unroll") for (int _i = 0; _i < 2; ++_i) \
;         __builtin_amdgcn_global_load_lds((const unsigned*)((const char*)(gbase) + (voff)[_i]), (PG8_LAS unsigned*)(lds + (bufoff) + ldsw + _i * 8192), 16, 0, 0); } while (0)
; #define PG8_LDA(dst, b, h) do { _Pragma("unroll") for (int m = 0; m < 4; ++m) _Pragma("unroll") for (int k = 0; k < 2; ++k) dst[m][k] = *(const PG8_LAS bf16x8*)(lds + PG8_SA(b, h) + aoff + m * 2048 + k * 1024); } while (0)
; #define PG8_LDB(dst, b, h) do { _Pragma("unroll") for (int n = 0; n < 2; ++n) _Pragma("unroll") for (int k = 0; k < 2; ++k) dst[n][k] = *(const PG8_LAS bf16x8*)(lds + PG8_SB(b, h) + boff + n * 2048 + k * 1024); } while (0)
; #define PG8_MMA(ai, bj, At, Bt) do { __builtin_amdgcn_s_setprio(1); _Pragma("unroll") for (int m = 0; m < 4; ++m) _Pragma("unroll") for (int n = 0; n < 2; ++n) _Pragma("unroll") for (int k = 0; k < 2; ++k) \
;         acc[ai][bj][m][n] = __builtin_amdgcn_mfma_f32_16x16x32_bf16(Bt[n][k], At[m][k], acc[ai][bj][m][n], 0, 0, 0); __builtin_amdgcn_s_setprio(0); } while (0)
; #define PG8_WAIT_V(n) asm volatile("s_waitcnt vmcnt(" #n ")" ::: "memory")
; #define PG8_WAIT_L(n) asm volatile("s_waitcnt lgkmcnt(" #n ")" ::: "memory")
; #define PG8_BAR __builtin_amdgcn_s_barrier()
; #define PG8_SCHED __builtin_amdgcn_sched_barrier(0)
; template <class Epi, class Sched, bool ALIGN_EPI = false, bool SP2 = false>
; __device__ __forceinline__ void gemm_phase(PG8_LAS unsigned char* lds, const Gemm g, const Sched& S, const Epi& E, volatile PG8_LAS unsigned* sw = nullptr) {
;     ...
;             PG8_LDB(B0, 0, 0); PG8_LDB(B1, 0, 1); PG8_SCHED; PG8_LDA(At, 0, 0); PG8_STAGE(PG8_SA(1, 1), a1 + hstep, voffA);
;             PG8_WAIT_V(8); PG8_WAIT_L(0); PG8_BAR; PG8_MMA(0, 0, At, B0); PG8_MMA(0, 1, At, B1); PG8_BAR; PG8_SCHED;
;             PG8_LDA(At, 0, 1); PG8_STAGE(PG8_SB(0, 0), b2, voffB); PG8_STAGE(PG8_SB(0, 1), b2 + hstep, voffB); PG8_STAGE(PG8_SA(0, 0), a2, voffA);
;             PG8_WAIT_V(8); PG8_WAIT_L(0); PG8_BAR; PG8_MMA(1, 0, At, B0); PG8_MMA(1, 1, At, B1); PG8_BAR; PG8_SCHED;
.LBB0_444:
	ds_read_b128 v[130:133], v174
	ds_read_b128 v[134:137], v174 offset:1024
	ds_read_b128 v[138:141], v174 offset:2048
	ds_read_b128 v[142:145], v174 offset:3072
	ds_read_b128 v[160:163], v175
	ds_read_b128 v[164:167], v175 offset:1024
	ds_read_b128 v[168:171], v175 offset:2048
	ds_read_b128 v[178:181], v175 offset:3072
	s_add_u32 s48, s46, 0x4000
	s_addc_u32 s49, s47, 0
	s_cmp_eq_u32 s80, 12
	s_cselect_b32 s52, s31, s48
	s_cselect_b32 s53, s9, s49
	s_cselect_b32 s50, s73, s74
	s_cselect_b32 s51, s23, s75
	s_add_u32 s48, s52, 0x8000
	s_addc_u32 s49, s53, 0
	v_lshl_add_u64 v[214:215], s[46:47], 0, v[156:157]
	s_add_i32 m0, s13, 0xc000
	ds_read_b128 v[182:185], v176
	ds_read_b128 v[186:189], v176 offset:1024
	ds_read_b128 v[190:193], v176 offset:2048
	ds_read_b128 v[194:197], v176 offset:3072
	ds_read_b128 v[198:201], v176 offset:4096
	ds_read_b128 v[202:205], v176 offset:5120
	ds_read_b128 v[206:209], v176 offset:6144
	ds_read_b128 v[210:213], v176 offset:7168
	global_load_lds_dwordx4 v[214:215], off
	v_lshl_add_u64 v[214:215], s[46:47], 0, v[158:159]
	s_add_i32 m0, s13, 0xe000
	s_nop 0
	global_load_lds_dwordx4 v[214:215], off
	s_waitcnt vmcnt(8)
	s_waitcnt lgkmcnt(0)
	s_barrier
	s_setprio 1
	s_waitcnt lgkmcnt(0)
	v_mfma_f32_16x16x32_bf16 v[126:129], v[130:133], v[182:185], v[126:129]
	v_mfma_f32_16x16x32_bf16 v[122:125], v[138:141], v[182:185], v[122:125]
	v_mfma_f32_16x16x32_bf16 v[118:121], v[130:133], v[190:193], v[118:121]
	v_mfma_f32_16x16x32_bf16 v[114:117], v[138:141], v[190:193], v[114:117]
	v_mfma_f32_16x16x32_bf16 v[110:113], v[130:133], v[198:201], v[110:113]
	v_mfma_f32_16x16x32_bf16 v[106:109], v[138:141], v[198:201], v[106:109]
	v_mfma_f32_16x16x32_bf16 v[102:105], v[130:133], v[206:209], v[102:105]
	v_mfma_f32_16x16x32_bf16 v[98:101], v[138:141], v[206:209], v[98:101]
	v_mfma_f32_16x16x32_bf16 v[126:129], v[134:137], v[186:189], v[126:129]
	v_mfma_f32_16x16x32_bf16 v[122:125], v[142:145], v[186:189], v[122:125]
	v_mfma_f32_16x16x32_bf16 v[118:121], v[134:137], v[194:197], v[118:121]
	v_mfma_f32_16x16x32_bf16 v[114:117], v[142:145], v[194:197], v[114:117]
	v_mfma_f32_16x16x32_bf16 v[110:113], v[134:137], v[202:205], v[110:113]
	v_mfma_f32_16x16x32_bf16 v[106:109], v[142:145], v[202:205], v[106:109]
	v_mfma_f32_16x16x32_bf16 v[102:105], v[134:137], v[210:213], v[102:105]
	v_mfma_f32_16x16x32_bf16 v[98:101], v[142:145], v[210:213], v[98:101]
	s_setprio 0
	s_setprio 1
	v_mfma_f32_16x16x32_bf16 v[66:69], v[160:163], v[182:185], v[66:69]
	v_mfma_f32_16x16x32_bf16 v[58:61], v[168:171], v[182:185], v[58:61]
	v_mfma_f32_16x16x32_bf16 v[54:57], v[160:163], v[190:193], v[54:57]
	v_mfma_f32_16x16x32_bf16 v[50:53], v[168:171], v[190:193], v[50:53]
	v_mfma_f32_16x16x32_bf16 v[46:49], v[160:163], v[198:201], v[46:49]
	v_mfma_f32_16x16x32_bf16 v[42:45], v[168:171], v[198:201], v[42:45]
	v_mfma_f32_16x16x32_bf16 v[38:41], v[160:163], v[206:209], v[38:41]
	v_mfma_f32_16x16x32_bf16 v[34:37], v[168:171], v[206:209], v[34:37]
	v_mfma_f32_16x16x32_bf16 v[66:69], v[164:167], v[186:189], v[66:69]
	v_mfma_f32_16x16x32_bf16 v[58:61], v[178:181], v[186:189], v[58:61]
	v_mfma_f32_16x16x32_bf16 v[54:57], v[164:167], v[194:197], v[54:57]
	v_mfma_f32_16x16x32_bf16 v[50:53], v[178:181], v[194:197], v[50:53]
	v_mfma_f32_16x16x32_bf16 v[46:49], v[164:167], v[202:205], v[46:49]
	v_mfma_f32_16x16x32_bf16 v[42:45], v[178:181], v[202:205], v[42:45]
	v_mfma_f32_16x16x32_bf16 v[38:41], v[164:167], v[210:213], v[38:41]
	v_mfma_f32_16x16x32_bf16 v[34:37], v[178:181], v[210:213], v[34:37]
	s_setprio 0
	s_barrier
	s_add_i32 s81, s57, s11
	v_lshl_add_u64 v[214:215], s[50:51], 0, v[150:151]
	s_mov_b32 m0, s81
	ds_read_b128 v[182:185], v176 offset:16384
	ds_read_b128 v[186:189], v176 offset:17408
	ds_read_b128 v[190:193], v176 offset:18432
	ds_read_b128 v[194:197], v176 offset:19456
	ds_read_b128 v[198:201], v176 offset:20480
	ds_read_b128 v[202:205], v176 offset:21504
	ds_read_b128 v[206:209], v176 offset:22528
	ds_read_b128 v[210:213], v176 offset:23552
	global_load_lds_dwordx4 v[214:215], off
	s_add_i32 m0, s81, 0x2000
	s_add_u32 s82, s50, 0x4000
	v_lshl_add_u64 v[214:215], s[50:51], 0, v[146:147]
	s_addc_u32 s83, s51, 0
	s_add_i32 s81, s58, s11
	global_load_lds_dwordx4 v[214:215], off
	v_lshl_add_u64 v[214:215], s[82:83], 0, v[150:151]
	s_mov_b32 m0, s81
	s_nop 0
	global_load_lds_dwordx4 v[214:215], off
	v_lshl_add_u64 v[214:215], s[82:83], 0, v[146:147]
	s_add_i32 m0, s81, 0x2000
	s_nop 0
	global_load_lds_dwordx4 v[214:215], off
	v_lshl_add_u64 v[214:215], s[52:53], 0, v[152:153]
	s_mov_b32 m0, s13
	s_nop 0
	global_load_lds_dwordx4 v[214:215], off
	v_lshl_add_u64 v[214:215], s[52:53], 0, v[148:149]
	s_mov_b32 m0, s14
	s_nop 0
	global_load_lds_dwordx4 v[214:215], off
	s_waitcnt vmcnt(8)
	s_waitcnt lgkmcnt(0)
	s_barrier
; #define PG8_STAGE(bufoff, gbase, voff) do { _Pragma("unroll") for (int _i = 0; _i < 2; ++_i) \
;         __builtin_amdgcn_global_load_lds((const unsigned*)((const char*)(gbase) + (voff)[_i]), (PG8_LAS unsigned*)(lds + (bufoff) + ldsw + _i * 8192), 16, 0, 0); } while (0)
; #define PG8_LDA(dst, b, h) do { _Pragma("unroll") for (int m = 0; m < 4; ++m) _Pragma("unroll") for (int k = 0; k < 2; ++k) dst[m][k] = *(const PG8_LAS bf16x8*)(lds + PG8_SA(b, h) + aoff + m * 2048 + k * 1024); } while (0)
; #define PG8_LDB(dst, b, h) do { _Pragma("unroll") for (int n = 0; n < 2; ++n) _Pragma("unroll") for (int k = 0; k < 2; ++k) dst[n][k] = *(const PG8_LAS bf16x8*)(lds + PG8_SB(b, h) + boff + n * 2048 + k * 1024); } while (0)
; #define PG8_MMA(ai, bj, At, Bt) do { __builtin_amdgcn_s_setprio(1); _Pragma("unroll") for (int m = 0; m < 4; ++m) _Pragma("unroll") for (int n = 0; n < 2; ++n) _Pragma("unroll") for (int k = 0; k < 2; ++k) \
;         acc[ai][bj][m][n] = __builtin_amdgcn_mfma_f32_16x16x32_bf16(Bt[n][k], At[m][k], acc[ai][bj][m][n], 0, 0, 0); __builtin_amdgcn_s_setprio(0); } while (0)
; #define PG8_WAIT_V(n) asm volatile("s_waitcnt vmcnt(" #n ")" ::: "memory")
; #define PG8_WAIT_L(n) asm volatile("s_waitcnt lgkmcnt(" #n ")" ::: "memory")
; #define PG8_BAR __builtin_amdgcn_s_barrier()
; #define PG8_SCHED __builtin_amdgcn_sched_barrier(0)
; template <class Epi, class Sched, bool ALIGN_EPI = false, bool SP2 = false>
; __device__ __forceinline__ void gemm_phase(PG8_LAS unsigned char* lds, const Gemm g, const Sched& S, const Epi& E, volatile PG8_LAS unsigned* sw = nullptr) {
;     ...
;             PG8_WAIT_V(8); PG8_WAIT_L(0); PG8_BAR; PG8_MMA(1, 0, At, B0); PG8_MMA(1, 1, At, B1); PG8_BAR; PG8_SCHED;
;             PG8_LDB(B0, 1, 0); PG8_LDB(B1, 1, 1); PG8_SCHED; PG8_LDA(At, 1, 0); PG8_STAGE(PG8_SA(0, 1), a2 + hstep, voffA);
;             PG8_WAIT_V(8); PG8_WAIT_L(0); PG8_BAR; PG8_MMA(0, 0, At, B0); PG8_MMA(0, 1, At, B1); PG8_BAR; PG8_SCHED;
	s_setprio 1
	s_waitcnt lgkmcnt(0)
	v_mfma_f32_16x16x32_bf16 v[94:97], v[130:133], v[182:185], v[94:97]
	v_mfma_f32_16x16x32_bf16 v[90:93], v[138:141], v[182:185], v[90:93]
	v_mfma_f32_16x16x32_bf16 v[86:89], v[130:133], v[190:193], v[86:89]
	v_mfma_f32_16x16x32_bf16 v[82:85], v[138:141], v[190:193], v[82:85]
	v_mfma_f32_16x16x32_bf16 v[78:81], v[130:133], v[198:201], v[78:81]
	v_mfma_f32_16x16x32_bf16 v[74:77], v[138:141], v[198:201], v[74:77]
	v_mfma_f32_16x16x32_bf16 v[70:73], v[130:133], v[206:209], v[70:73]
	v_mfma_f32_16x16x32_bf16 v[62:65], v[138:141], v[206:209], v[62:65]
	v_mfma_f32_16x16x32_bf16 v[94:97], v[134:137], v[186:189], v[94:97]
	v_mfma_f32_16x16x32_bf16 v[90:93], v[142:145], v[186:189], v[90:93]
	v_mfma_f32_16x16x32_bf16 v[86:89], v[134:137], v[194:197], v[86:89]
	v_mfma_f32_16x16x32_bf16 v[82:85], v[142:145], v[194:197], v[82:85]
	v_mfma_f32_16x16x32_bf16 v[78:81], v[134:137], v[202:205], v[78:81]
	v_mfma_f32_16x16x32_bf16 v[74:77], v[142:145], v[202:205], v[74:77]
	v_mfma_f32_16x16x32_bf16 v[70:73], v[134:137], v[210:213], v[70:73]
	v_mfma_f32_16x16x32_bf16 v[62:65], v[142:145], v[210:213], v[62:65]
	s_setprio 0
	s_setprio 1
	v_mfma_f32_16x16x32_bf16 v[30:33], v[160:163], v[182:185], v[30:33]
	v_mfma_f32_16x16x32_bf16 v[26:29], v[168:171], v[182:185], v[26:29]
	v_mfma_f32_16x16x32_bf16 v[22:25], v[160:163], v[190:193], v[22:25]
	v_mfma_f32_16x16x32_bf16 v[18:21], v[168:171], v[190:193], v[18:21]
	v_mfma_f32_16x16x32_bf16 v[14:17], v[160:163], v[198:201], v[14:17]
	v_mfma_f32_16x16x32_bf16 v[10:13], v[168:171], v[198:201], v[10:13]
	v_mfma_f32_16x16x32_bf16 v[6:9], v[160:163], v[206:209], v[6:9]
	v_mfma_f32_16x16x32_bf16 v[2:5], v[168:171], v[206:209], v[2:5]
	v_mfma_f32_16x16x32_bf16 v[30:33], v[164:167], v[186:189], v[30:33]
	v_mfma_f32_16x16x32_bf16 v[26:29], v[178:181], v[186:189], v[26:29]
	v_mfma_f32_16x16x32_bf16 v[22:25], v[164:167], v[194:197], v[22:25]
	v_mfma_f32_16x16x32_bf16 v[18:21], v[178:181], v[194:197], v[18:21]
	v_mfma_f32_16x16x32_bf16 v[14:17], v[164:167], v[202:205], v[14:17]
	v_mfma_f32_16x16x32_bf16 v[10:13], v[178:181], v[202:205], v[10:13]
	v_mfma_f32_16x16x32_bf16 v[6:9], v[164:167], v[210:213], v[6:9]
	v_mfma_f32_16x16x32_bf16 v[2:5], v[178:181], v[210:213], v[2:5]
	s_setprio 0
	s_barrier
	s_add_i32 s81, 0, 0x18000
	s_add_i32 s82, 0, 0x1c000
	v_add_u32_e32 v142, s81, v173
	v_add_u32_e32 v154, s82, v173
	ds_read_b128 v[130:133], v142
	ds_read_b128 v[134:137], v142 offset:1024
	ds_read_b128 v[138:141], v142 offset:2048
	ds_read_b128 v[142:145], v142 offset:3072
	ds_read_b128 v[160:163], v154
	ds_read_b128 v[164:167], v154 offset:1024
	ds_read_b128 v[168:171], v154 offset:2048
	ds_read_b128 v[178:181], v154 offset:3072
	s_add_u32 s52, s52, 0x4000
	s_addc_u32 s53, s53, 0
	s_mov_b32 m0, s15
	v_lshl_add_u64 v[214:215], s[52:53], 0, v[152:153]
	ds_read_b128 v[182:185], v176 offset:32768
	ds_read_b128 v[186:189], v176 offset:33792
	ds_read_b128 v[190:193], v176 offset:34816
	ds_read_b128 v[194:197], v176 offset:35840
	ds_read_b128 v[198:201], v176 offset:36864
	ds_read_b128 v[202:205], v176 offset:37888
	ds_read_b128 v[206:209], v176 offset:38912
	ds_read_b128 v[210:213], v176 offset:39936
	global_load_lds_dwordx4 v[214:215], off
	v_lshl_add_u64 v[214:215], s[52:53], 0, v[148:149]
	s_mov_b32 m0, s33
	s_nop 0
	global_load_lds_dwordx4 v[214:215], off
	s_waitcnt vmcnt(8)
	s_waitcnt lgkmcnt(0)
	s_barrier
	s_setprio 1
	s_waitcnt lgkmcnt(0)
	v_mfma_f32_16x16x32_bf16 v[126:129], v[130:133], v[182:185], v[126:129]
	v_mfma_f32_16x16x32_bf16 v[122:125], v[138:141], v[182:185], v[122:125]
	v_mfma_f32_16x16x32_bf16 v[118:121], v[130:133], v[190:193], v[118:121]
	v_mfma_f32_16x16x32_bf16 v[114:117], v[138:141], v[190:193], v[114:117]
	v_mfma_f32_16x16x32_bf16 v[110:113], v[130:133], v[198:201], v[110:113]
	v_mfma_f32_16x16x32_bf16 v[106:109], v[138:141], v[198:201], v[106:109]
	v_mfma_f32_16x16x32_bf16 v[102:105], v[130:133], v[206:209], v[102:105]
	v_mfma_f32_16x16x32_bf16 v[98:101], v[138:141], v[206:209], v[98:101]
	v_mfma_f32_16x16x32_bf16 v[126:129], v[134:137], v[186:189], v[126:129]
	v_mfma_f32_16x16x32_bf16 v[122:125], v[142:145], v[186:189], v[122:125]
	v_mfma_f32_16x16x32_bf16 v[118:121], v[134:137], v[194:197], v[118:121]
	v_mfma_f32_16x16x32_bf16 v[114:117], v[142:145], v[194:197], v[114:117]
	v_mfma_f32_16x16x32_bf16 v[110:113], v[134:137], v[202:205], v[110:113]
	v_mfma_f32_16x16x32_bf16 v[106:109], v[142:145], v[202:205], v[106:109]
	v_mfma_f32_16x16x32_bf16 v[102:105], v[134:137], v[210:213], v[102:105]
	v_mfma_f32_16x16x32_bf16 v[98:101], v[142:145], v[210:213], v[98:101]
	s_setprio 0
	s_setprio 1
	v_mfma_f32_16x16x32_bf16 v[66:69], v[160:163], v[182:185], v[66:69]
	v_mfma_f32_16x16x32_bf16 v[58:61], v[168:171], v[182:185], v[58:61]
	v_mfma_f32_16x16x32_bf16 v[54:57], v[160:163], v[190:193], v[54:57]
	v_mfma_f32_16x16x32_bf16 v[50:53], v[168:171], v[190:193], v[50:53]
	v_mfma_f32_16x16x32_bf16 v[46:49], v[160:163], v[198:201], v[46:49]
	v_mfma_f32_16x16x32_bf16 v[42:45], v[168:171], v[198:201], v[42:45]
	v_mfma_f32_16x16x32_bf16 v[38:41], v[160:163], v[206:209], v[38:41]
	v_mfma_f32_16x16x32_bf16 v[34:37], v[168:171], v[206:209], v[34:37]
	v_mfma_f32_16x16x32_bf16 v[66:69], v[164:167], v[186:189], v[66:69]
	v_mfma_f32_16x16x32_bf16 v[58:61], v[178:181], v[186:189], v[58:61]
	v_mfma_f32_16x16x32_bf16 v[54:57], v[164:167], v[194:197], v[54:57]
	v_mfma_f32_16x16x32_bf16 v[50:53], v[178:181], v[194:197], v[50:53]
	v_mfma_f32_16x16x32_bf16 v[46:49], v[164:167], v[202:205], v[46:49]
	v_mfma_f32_16x16x32_bf16 v[42:45], v[178:181], v[202:205], v[42:45]
	v_mfma_f32_16x16x32_bf16 v[38:41], v[164:167], v[210:213], v[38:41]
	v_mfma_f32_16x16x32_bf16 v[34:37], v[178:181], v[210:213], v[34:37]
	s_setprio 0
	s_barrier
; #define PG8_STAGE(bufoff, gbase, voff) do { _Pragma("unroll") for (int _i = 0; _i < 2; ++_i) \
;         __builtin_amdgcn_global_load_lds((const unsigned*)((const char*)(gbase) + (voff)[_i]), (PG8_LAS unsigned*)(lds + (bufoff) + ldsw + _i * 8192), 16, 0, 0); } while (0)
; #define PG8_LDA(dst, b, h) do { _Pragma("unroll") for (int m = 0; m < 4; ++m) _Pragma("unroll") for (int k = 0; k < 2; ++k) dst[m][k] = *(const PG8_LAS bf16x8*)(lds + PG8_SA(b, h) + aoff + m * 2048 + k * 1024); } while (0)
; #define PG8_MMA(ai, bj, At, Bt) do { __builtin_amdgcn_s_setprio(1); _Pragma("unroll") for (int m = 0; m < 4; ++m) _Pragma("unroll") for (int n = 0; n < 2; ++n) _Pragma("unroll") for (int k = 0; k < 2; ++k) \
;         acc[ai][bj][m][n] = __builtin_amdgcn_mfma_f32_16x16x32_bf16(Bt[n][k], At[m][k], acc[ai][bj][m][n], 0, 0, 0); __builtin_amdgcn_s_setprio(0); } while (0)
; #define PG8_WAIT_V(n) asm volatile("s_waitcnt vmcnt(" #n ")" ::: "memory")
; #define PG8_WAIT_L(n) asm volatile("s_waitcnt lgkmcnt(" #n ")" ::: "memory")
; #define PG8_BAR __builtin_amdgcn_s_barrier()
; #define PG8_SCHED __builtin_amdgcn_sched_barrier(0)
; template <class Epi, class Sched, bool ALIGN_EPI = false, bool SP2 = false>
; __device__ __forceinline__ void gemm_phase(PG8_LAS unsigned char* lds, const Gemm g, const Sched& S, const Epi& E, volatile PG8_LAS unsigned* sw = nullptr) {
;     ...
;             PG8_LDA(At, 1, 1); PG8_STAGE(PG8_SB(1, 0), b3, voffB); PG8_STAGE(PG8_SB(1, 1), b3 + hstep, voffB); PG8_STAGE(PG8_SA(1, 0), a3, voffA);
;             PG8_WAIT_V(8); PG8_WAIT_L(0); PG8_BAR; PG8_MMA(1, 0, At, B0); PG8_MMA(1, 1, At, B1); PG8_BAR; PG8_SCHED;
;     ...
;         if constexpr (ALIGN_EPI) { if (wr == 0) PG8_BAR; }
	s_add_u32 s52, s50, 0x8000
	s_addc_u32 s53, s51, 0
	s_add_i32 s81, s81, s11
	v_lshl_add_u64 v[214:215], s[52:53], 0, v[150:151]
	s_mov_b32 m0, s81
	ds_read_b128 v[182:185], v176 offset:49152
	ds_read_b128 v[186:189], v176 offset:50176
	ds_read_b128 v[190:193], v176 offset:51200
	ds_read_b128 v[194:197], v176 offset:52224
	ds_read_b128 v[198:201], v176 offset:53248
	ds_read_b128 v[202:205], v176 offset:54272
	ds_read_b128 v[206:209], v176 offset:55296
	ds_read_b128 v[210:213], v176 offset:56320
	global_load_lds_dwordx4 v[214:215], off
	s_add_i32 m0, s81, 0x2000
	s_add_u32 s50, s50, 0xc000
	v_lshl_add_u64 v[214:215], s[52:53], 0, v[146:147]
	s_addc_u32 s51, s51, 0
	s_add_i32 s52, s82, s11
	global_load_lds_dwordx4 v[214:215], off
	v_lshl_add_u64 v[214:215], s[50:51], 0, v[150:151]
	s_mov_b32 m0, s52
	s_nop 0
	global_load_lds_dwordx4 v[214:215], off
	v_lshl_add_u64 v[214:215], s[50:51], 0, v[146:147]
	s_add_i32 m0, s52, 0x2000
	s_nop 0
	global_load_lds_dwordx4 v[214:215], off
	v_lshl_add_u64 v[214:215], s[48:49], 0, v[152:153]
	s_mov_b32 m0, s41
	s_nop 0
	global_load_lds_dwordx4 v[214:215], off
	v_lshl_add_u64 v[214:215], s[48:49], 0, v[148:149]
	s_mov_b32 m0, s42
	s_nop 0
	global_load_lds_dwordx4 v[214:215], off
	s_waitcnt vmcnt(8)
	s_waitcnt lgkmcnt(0)
	s_barrier
	s_setprio 1
	s_waitcnt lgkmcnt(0)
	v_mfma_f32_16x16x32_bf16 v[94:97], v[130:133], v[182:185], v[94:97]
	v_mfma_f32_16x16x32_bf16 v[90:93], v[138:141], v[182:185], v[90:93]
	v_mfma_f32_16x16x32_bf16 v[86:89], v[130:133], v[190:193], v[86:89]
	v_mfma_f32_16x16x32_bf16 v[82:85], v[138:141], v[190:193], v[82:85]
	v_mfma_f32_16x16x32_bf16 v[78:81], v[130:133], v[198:201], v[78:81]
	v_mfma_f32_16x16x32_bf16 v[74:77], v[138:141], v[198:201], v[74:77]
	v_mfma_f32_16x16x32_bf16 v[70:73], v[130:133], v[206:209], v[70:73]
	v_mfma_f32_16x16x32_bf16 v[62:65], v[138:141], v[206:209], v[62:65]
	v_mfma_f32_16x16x32_bf16 v[94:97], v[134:137], v[186:189], v[94:97]
	v_mfma_f32_16x16x32_bf16 v[90:93], v[142:145], v[186:189], v[90:93]
	v_mfma_f32_16x16x32_bf16 v[86:89], v[134:137], v[194:197], v[86:89]
	v_mfma_f32_16x16x32_bf16 v[82:85], v[142:145], v[194:197], v[82:85]
	v_mfma_f32_16x16x32_bf16 v[78:81], v[134:137], v[202:205], v[78:81]
	v_mfma_f32_16x16x32_bf16 v[74:77], v[142:145], v[202:205], v[74:77]
	v_mfma_f32_16x16x32_bf16 v[70:73], v[134:137], v[210:213], v[70:73]
	v_mfma_f32_16x16x32_bf16 v[62:65], v[142:145], v[210:213], v[62:65]
	s_setprio 0
	s_setprio 1
	v_mfma_f32_16x16x32_bf16 v[30:33], v[160:163], v[182:185], v[30:33]
	v_mfma_f32_16x16x32_bf16 v[26:29], v[168:171], v[182:185], v[26:29]
	v_mfma_f32_16x16x32_bf16 v[22:25], v[160:163], v[190:193], v[22:25]
	v_mfma_f32_16x16x32_bf16 v[18:21], v[168:171], v[190:193], v[18:21]
	v_mfma_f32_16x16x32_bf16 v[14:17], v[160:163], v[198:201], v[14:17]
	v_mfma_f32_16x16x32_bf16 v[10:13], v[168:171], v[198:201], v[10:13]
	v_mfma_f32_16x16x32_bf16 v[6:9], v[160:163], v[206:209], v[6:9]
	v_mfma_f32_16x16x32_bf16 v[2:5], v[168:171], v[206:209], v[2:5]
	v_mfma_f32_16x16x32_bf16 v[30:33], v[164:167], v[186:189], v[30:33]
	v_mfma_f32_16x16x32_bf16 v[26:29], v[178:181], v[186:189], v[26:29]
	v_mfma_f32_16x16x32_bf16 v[22:25], v[164:167], v[194:197], v[22:25]
	v_mfma_f32_16x16x32_bf16 v[18:21], v[178:181], v[194:197], v[18:21]
	v_mfma_f32_16x16x32_bf16 v[14:17], v[164:167], v[202:205], v[14:17]
	v_mfma_f32_16x16x32_bf16 v[10:13], v[178:181], v[202:205], v[10:13]
	v_mfma_f32_16x16x32_bf16 v[6:9], v[164:167], v[210:213], v[6:9]
	v_mfma_f32_16x16x32_bf16 v[2:5], v[178:181], v[210:213], v[2:5]
	s_setprio 0
	s_barrier
	s_add_i32 s80, s80, 2
	s_add_u32 s46, s46, 0x10000
	s_addc_u32 s47, s47, 0
	s_add_u32 s74, s74, 0x10000
	s_addc_u32 s75, s75, 0
	s_cmp_gt_u32 s80, 13
	s_cbranch_scc0 .LBB0_444
	s_and_b64 vcc, exec, s[4:5]
	s_cbranch_vccz .LBB0_447
	s_cmp_lg_u32 s98, 0
	s_cbranch_scc1 .LBB0_447
	s_barrier

; #define PG8_BAR __builtin_amdgcn_s_barrier()
; template <class Epi, class Sched, bool ALIGN_EPI = false, bool SP2 = false>
; __device__ __forceinline__ void gemm_phase(PG8_LAS unsigned char* lds, const Gemm g, const Sched& S, const Epi& E, volatile PG8_LAS unsigned* sw = nullptr) {
;     ...
;         if constexpr (Epi::PREFETCH) { E.run(acc, cur, wr, wc, fr, fq, ui & 1); if (has_next) E.prefetch(nxt, (ui + 1) & 1, wid, lane); S.done(cur); }
;         else if constexpr (!Epi::AFTER_DRAIN) { E(acc, cur, wr, wc, fr, fq); S.done(cur); }
;         if (sw) { __builtin_amdgcn_sched_barrier(0); const unsigned long long t1 = __builtin_amdgcn_s_memrealtime(); if (threadIdx.x == 0) sw[1] += (unsigned)(t1 - sw_t); __builtin_amdgcn_sched_barrier(0); }
;         if (!has_next) break;
; #pragma unroll
;         for (int a = 0; a < 2; ++a)
; #pragma unroll
;             for (int b = 0; b < 2; ++b)
; #pragma unroll
;                 for (int m = 0; m < 4; ++m)
; #pragma unroll
;                     for (int n = 0; n < 2; ++n) acc[a][b][m][n] = (f32x4){0.f, 0.f, 0.f, 0.f};
;         cur = nxt; cA = nA; cB = nB; ++ui;
;         if constexpr (ALIGN_EPI) { if (wr == 1) PG8_BAR; }
.LBB0_453:
	s_or_b64 exec, exec, s[30:31]
	s_andn2_b64 vcc, exec, s[26:27]
	s_mov_b64 s[26:27], -1
	s_cbranch_vccnz .LBB0_440
	s_andn2_b64 vcc, exec, s[0:1]
	s_cbranch_vccnz .LBB0_439
	s_branch .LBB0_439

;     __device__ bool next(int i, pg8::Unit& u) const { const int L = i * cph + k; if (L >= nunits) return false; const int nig = 8 * nN, gid = L / nig, w = L % nig; u.pm = 16 * xh + 8 * gid + (w & 7); u.pn = w >> 3; return true; }
; template <class Epi, class Sched, bool ALIGN_EPI = false, bool SP2 = false>
; __device__ __forceinline__ void gemm_phase(PG8_LAS unsigned char* lds, const Gemm g, const Sched& S, const Epi& E, volatile PG8_LAS unsigned* sw = nullptr) {
;     ...
;         const bool has_next = S.next(ui + 1, nxt);
;         const char* nA = has_next ? (const char*)g.A + (size_t)nxt.pm * tstep : cA; const char* nB = has_next ? (const char*)g.Bt + (size_t)nxt.pn * tstep : cB;
.LBB0_696:
	s_add_i32 s29, s29, 1
	s_mul_i32 s0, s29, s76
	s_add_i32 s0, s0, s97
	s_cmp_lt_i32 s0, 64
	s_cselect_b64 s[6:7], -1, 0
	s_cselect_b32 s98, 1, 0
	s_cmp_gt_i32 s0, 63
	s_cbranch_scc1 .LBB0_698
	s_ashr_i32 s1, s0, 31
	s_lshr_b32 s1, s1, 27
	s_add_i32 s1, s0, s1
	s_ashr_i32 s8, s1, 5
	s_andn2_b32 s1, s1, 31
	s_sub_i32 s0, s0, s1
	s_lshl_b32 s1, s8, 3
	s_add_i32 s1, s1, s77
	s_and_b32 s8, s0, 7
	s_or_b32 s53, s1, s8
	s_ashr_i32 s52, s0, 3

; #define PG8_STAGE(bufoff, gbase, voff) do { _Pragma("unroll") for (int _i = 0; _i < 2; ++_i) \
;         __builtin_amdgcn_global_load_lds((const unsigned*)((const char*)(gbase) + (voff)[_i]), (PG8_LAS unsigned*)(lds + (bufoff) + ldsw + _i * 8192), 16, 0, 0); } while (0)
; #define PG8_LDA(dst, b, h) do { _Pragma("unroll") for (int m = 0; m < 4; ++m) _Pragma("unroll") for (int k = 0; k < 2; ++k) dst[m][k] = *(const PG8_LAS bf16x8*)(lds + PG8_SA(b, h) + aoff + m * 2048 + k * 1024); } while (0)
; #define PG8_LDB(dst, b, h) do { _Pragma("unroll") for (int n = 0; n < 2; ++n) _Pragma("unroll") for (int k = 0; k < 2; ++k) dst[n][k] = *(const PG8_LAS bf16x8*)(lds + PG8_SB(b, h) + boff + n * 2048 + k * 1024); } while (0)
; #define PG8_MMA(ai, bj, At, Bt) do { __builtin_amdgcn_s_setprio(1); _Pragma("unroll") for (int m = 0; m < 4; ++m) _Pragma("unroll") for (int n = 0; n < 2; ++n) _Pragma("unroll") for (int k = 0; k < 2; ++k) \
;         acc[ai][bj][m][n] = __builtin_amdgcn_mfma_f32_16x16x32_bf16(Bt[n][k], At[m][k], acc[ai][bj][m][n], 0, 0, 0); __builtin_amdgcn_s_setprio(0); } while (0)
; #define PG8_WAIT_V(n) asm volatile("s_waitcnt vmcnt(" #n ")" ::: "memory")
; #define PG8_WAIT_L(n) asm volatile("s_waitcnt lgkmcnt(" #n ")" ::: "memory")
; #define PG8_BAR __builtin_amdgcn_s_barrier()
; #define PG8_SCHED __builtin_amdgcn_sched_barrier(0)
; template <class Epi, class Sched, bool ALIGN_EPI = false, bool SP2 = false>
; __device__ __forceinline__ void gemm_phase(PG8_LAS unsigned char* lds, const Gemm g, const Sched& S, const Epi& E, volatile PG8_LAS unsigned* sw = nullptr) {
;     ...
;             PG8_LDB(B0, 0, 0); PG8_LDB(B1, 0, 1); PG8_SCHED; PG8_LDA(At, 0, 0); PG8_STAGE(PG8_SA(1, 1), a1 + hstep, voffA);
;             PG8_WAIT_V(8); PG8_WAIT_L(0); PG8_BAR; PG8_MMA(0, 0, At, B0); PG8_MMA(0, 1, At, B1); PG8_BAR; PG8_SCHED;
;             PG8_LDA(At, 0, 1); PG8_STAGE(PG8_SB(0, 0), b2, voffB); PG8_STAGE(PG8_SB(0, 1), b2 + hstep, voffB); PG8_STAGE(PG8_SA(0, 0), a2, voffA);
;             PG8_WAIT_V(8); PG8_WAIT_L(0); PG8_BAR; PG8_MMA(1, 0, At, B0); PG8_MMA(1, 1, At, B1); PG8_BAR; PG8_SCHED;
.LBB0_703:
	ds_read_b128 v[128:131], v221
	ds_read_b128 v[132:135], v221 offset:1024
	ds_read_b128 v[136:139], v221 offset:2048
	ds_read_b128 v[140:143], v221 offset:3072
	ds_read_b128 v[144:147], v222
	ds_read_b128 v[148:151], v222 offset:1024
	ds_read_b128 v[152:155], v222 offset:2048
	ds_read_b128 v[156:159], v222 offset:3072
	s_add_u32 s18, s14, 0x4000
	s_addc_u32 s19, s15, 0
	s_cmp_eq_u32 s54, 40
	s_cselect_b32 s22, s6, s18
	s_cselect_b32 s23, s7, s19
	s_cselect_b32 s20, s8, s11
	s_cselect_b32 s21, s9, s13
	s_add_u32 s18, s22, 0x8000
	s_addc_u32 s19, s23, 0
	v_lshl_add_u64 v[192:193], s[14:15], 0, v[214:215]
	s_add_i32 m0, s25, 0xc000
	ds_read_b128 v[160:163], v223
	ds_read_b128 v[164:167], v223 offset:1024
	ds_read_b128 v[168:171], v223 offset:2048
	ds_read_b128 v[172:175], v223 offset:3072
	ds_read_b128 v[176:179], v223 offset:4096
	ds_read_b128 v[180:183], v223 offset:5120
	ds_read_b128 v[184:187], v223 offset:6144
	ds_read_b128 v[188:191], v223 offset:7168
	global_load_lds_dwordx4 v[192:193], off
	v_lshl_add_u64 v[192:193], s[14:15], 0, v[216:217]
	s_add_i32 m0, s25, 0xe000
	s_nop 0
	global_load_lds_dwordx4 v[192:193], off
	s_waitcnt vmcnt(8)
	s_waitcnt lgkmcnt(0)
	s_barrier
	s_setprio 1
	s_waitcnt lgkmcnt(0)
	v_mfma_f32_16x16x32_bf16 v[124:127], v[128:131], v[160:163], v[124:127]
	v_mfma_f32_16x16x32_bf16 v[120:123], v[136:139], v[160:163], v[120:123]
	v_mfma_f32_16x16x32_bf16 v[116:119], v[128:131], v[168:171], v[116:119]
	v_mfma_f32_16x16x32_bf16 v[112:115], v[136:139], v[168:171], v[112:115]
	v_mfma_f32_16x16x32_bf16 v[108:111], v[128:131], v[176:179], v[108:111]
	v_mfma_f32_16x16x32_bf16 v[104:107], v[136:139], v[176:179], v[104:107]
	v_mfma_f32_16x16x32_bf16 v[100:103], v[128:131], v[184:187], v[100:103]
	v_mfma_f32_16x16x32_bf16 v[96:99], v[136:139], v[184:187], v[96:99]
	v_mfma_f32_16x16x32_bf16 v[124:127], v[132:135], v[164:167], v[124:127]
	v_mfma_f32_16x16x32_bf16 v[120:123], v[140:143], v[164:167], v[120:123]
	v_mfma_f32_16x16x32_bf16 v[116:119], v[132:135], v[172:175], v[116:119]
	v_mfma_f32_16x16x32_bf16 v[112:115], v[140:143], v[172:175], v[112:115]
	v_mfma_f32_16x16x32_bf16 v[108:111], v[132:135], v[180:183], v[108:111]
	v_mfma_f32_16x16x32_bf16 v[104:107], v[140:143], v[180:183], v[104:107]
	v_mfma_f32_16x16x32_bf16 v[100:103], v[132:135], v[188:191], v[100:103]
	v_mfma_f32_16x16x32_bf16 v[96:99], v[140:143], v[188:191], v[96:99]
	s_setprio 0
	s_setprio 1
	v_mfma_f32_16x16x32_bf16 v[68:71], v[144:147], v[160:163], v[68:71]
	v_mfma_f32_16x16x32_bf16 v[60:63], v[152:155], v[160:163], v[60:63]
	v_mfma_f32_16x16x32_bf16 v[52:55], v[144:147], v[168:171], v[52:55]
	v_mfma_f32_16x16x32_bf16 v[48:51], v[152:155], v[168:171], v[48:51]
	v_mfma_f32_16x16x32_bf16 v[44:47], v[144:147], v[176:179], v[44:47]
	v_mfma_f32_16x16x32_bf16 v[40:43], v[152:155], v[176:179], v[40:43]
	v_mfma_f32_16x16x32_bf16 v[36:39], v[144:147], v[184:187], v[36:39]
	v_mfma_f32_16x16x32_bf16 v[32:35], v[152:155], v[184:187], v[32:35]
	v_mfma_f32_16x16x32_bf16 v[68:71], v[148:151], v[164:167], v[68:71]
	v_mfma_f32_16x16x32_bf16 v[60:63], v[156:159], v[164:167], v[60:63]
	v_mfma_f32_16x16x32_bf16 v[52:55], v[148:151], v[172:175], v[52:55]
	v_mfma_f32_16x16x32_bf16 v[48:51], v[156:159], v[172:175], v[48:51]
	v_mfma_f32_16x16x32_bf16 v[44:47], v[148:151], v[180:183], v[44:47]
	v_mfma_f32_16x16x32_bf16 v[40:43], v[156:159], v[180:183], v[40:43]
	v_mfma_f32_16x16x32_bf16 v[36:39], v[148:151], v[188:191], v[36:39]
	v_mfma_f32_16x16x32_bf16 v[32:35], v[156:159], v[188:191], v[32:35]
	s_setprio 0
	s_barrier
	s_add_i32 s55, s40, s24
	v_lshl_add_u64 v[192:193], s[20:21], 0, v[208:209]
	s_mov_b32 m0, s55
	ds_read_b128 v[160:163], v223 offset:16384
	ds_read_b128 v[164:167], v223 offset:17408
	ds_read_b128 v[168:171], v223 offset:18432
	ds_read_b128 v[172:175], v223 offset:19456
	ds_read_b128 v[176:179], v223 offset:20480
	ds_read_b128 v[180:183], v223 offset:21504
	ds_read_b128 v[184:187], v223 offset:22528
	ds_read_b128 v[188:191], v223 offset:23552
	global_load_lds_dwordx4 v[192:193], off
	s_add_i32 m0, s55, 0x2000
	s_add_u32 s56, s20, 0x4000
	v_lshl_add_u64 v[192:193], s[20:21], 0, v[204:205]
	s_addc_u32 s57, s21, 0
	s_add_i32 s55, s41, s24
	global_load_lds_dwordx4 v[192:193], off
	v_lshl_add_u64 v[192:193], s[56:57], 0, v[208:209]
	s_mov_b32 m0, s55
	s_nop 0
	global_load_lds_dwordx4 v[192:193], off
	v_lshl_add_u64 v[192:193], s[56:57], 0, v[204:205]
	s_add_i32 m0, s55, 0x2000
	s_nop 0
	global_load_lds_dwordx4 v[192:193], off
	v_lshl_add_u64 v[192:193], s[22:23], 0, v[210:211]
	s_mov_b32 m0, s25
	s_nop 0
	global_load_lds_dwordx4 v[192:193], off
	v_lshl_add_u64 v[192:193], s[22:23], 0, v[206:207]
	s_mov_b32 m0, s26
	s_nop 0
	global_load_lds_dwordx4 v[192:193], off
	s_waitcnt vmcnt(8)
	s_waitcnt lgkmcnt(0)
	s_barrier
; #define PG8_STAGE(bufoff, gbase, voff) do { _Pragma("unroll") for (int _i = 0; _i < 2; ++_i) \
;         __builtin_amdgcn_global_load_lds((const unsigned*)((const char*)(gbase) + (voff)[_i]), (PG8_LAS unsigned*)(lds + (bufoff) + ldsw + _i * 8192), 16, 0, 0); } while (0)
; #define PG8_LDA(dst, b, h) do { _Pragma("unroll") for (int m = 0; m < 4; ++m) _Pragma("unroll") for (int k = 0; k < 2; ++k) dst[m][k] = *(const PG8_LAS bf16x8*)(lds + PG8_SA(b, h) + aoff + m * 2048 + k * 1024); } while (0)
; #define PG8_LDB(dst, b, h) do { _Pragma("unroll") for (int n = 0; n < 2; ++n) _Pragma("unroll") for (int k = 0; k < 2; ++k) dst[n][k] = *(const PG8_LAS bf16x8*)(lds + PG8_SB(b, h) + boff + n * 2048 + k * 1024); } while (0)
; #define PG8_MMA(ai, bj, At, Bt) do { __builtin_amdgcn_s_setprio(1); _Pragma("unroll") for (int m = 0; m < 4; ++m) _Pragma("unroll") for (int n = 0; n < 2; ++n) _Pragma("unroll") for (int k = 0; k < 2; ++k) \
;         acc[ai][bj][m][n] = __builtin_amdgcn_mfma_f32_16x16x32_bf16(Bt[n][k], At[m][k], acc[ai][bj][m][n], 0, 0, 0); __builtin_amdgcn_s_setprio(0); } while (0)
; #define PG8_WAIT_V(n) asm volatile("s_waitcnt vmcnt(" #n ")" ::: "memory")
; #define PG8_WAIT_L(n) asm volatile("s_waitcnt lgkmcnt(" #n ")" ::: "memory")
; #define PG8_BAR __builtin_amdgcn_s_barrier()
; #define PG8_SCHED __builtin_amdgcn_sched_barrier(0)
; template <class Epi, class Sched, bool ALIGN_EPI = false, bool SP2 = false>
; __device__ __forceinline__ void gemm_phase(PG8_LAS unsigned char* lds, const Gemm g, const Sched& S, const Epi& E, volatile PG8_LAS unsigned* sw = nullptr) {
;     ...
;             PG8_WAIT_V(8); PG8_WAIT_L(0); PG8_BAR; PG8_MMA(1, 0, At, B0); PG8_MMA(1, 1, At, B1); PG8_BAR; PG8_SCHED;
;             PG8_LDB(B0, 1, 0); PG8_LDB(B1, 1, 1); PG8_SCHED; PG8_LDA(At, 1, 0); PG8_STAGE(PG8_SA(0, 1), a2 + hstep, voffA);
;             PG8_WAIT_V(8); PG8_WAIT_L(0); PG8_BAR; PG8_MMA(0, 0, At, B0); PG8_MMA(0, 1, At, B1); PG8_BAR; PG8_SCHED;
	s_setprio 1
	s_waitcnt lgkmcnt(0)
	v_mfma_f32_16x16x32_bf16 v[92:95], v[128:131], v[160:163], v[92:95]
	v_mfma_f32_16x16x32_bf16 v[88:91], v[136:139], v[160:163], v[88:91]
	v_mfma_f32_16x16x32_bf16 v[84:87], v[128:131], v[168:171], v[84:87]
	v_mfma_f32_16x16x32_bf16 v[80:83], v[136:139], v[168:171], v[80:83]
	v_mfma_f32_16x16x32_bf16 v[76:79], v[128:131], v[176:179], v[76:79]
	v_mfma_f32_16x16x32_bf16 v[72:75], v[136:139], v[176:179], v[72:75]
	v_mfma_f32_16x16x32_bf16 v[64:67], v[128:131], v[184:187], v[64:67]
	v_mfma_f32_16x16x32_bf16 v[56:59], v[136:139], v[184:187], v[56:59]
	v_mfma_f32_16x16x32_bf16 v[92:95], v[132:135], v[164:167], v[92:95]
	v_mfma_f32_16x16x32_bf16 v[88:91], v[140:143], v[164:167], v[88:91]
	v_mfma_f32_16x16x32_bf16 v[84:87], v[132:135], v[172:175], v[84:87]
	v_mfma_f32_16x16x32_bf16 v[80:83], v[140:143], v[172:175], v[80:83]
	v_mfma_f32_16x16x32_bf16 v[76:79], v[132:135], v[180:183], v[76:79]
	v_mfma_f32_16x16x32_bf16 v[72:75], v[140:143], v[180:183], v[72:75]
	v_mfma_f32_16x16x32_bf16 v[64:67], v[132:135], v[188:191], v[64:67]
	v_mfma_f32_16x16x32_bf16 v[56:59], v[140:143], v[188:191], v[56:59]
	s_setprio 0
	s_setprio 1
	v_mfma_f32_16x16x32_bf16 v[28:31], v[144:147], v[160:163], v[28:31]
	v_mfma_f32_16x16x32_bf16 v[24:27], v[152:155], v[160:163], v[24:27]
	v_mfma_f32_16x16x32_bf16 v[20:23], v[144:147], v[168:171], v[20:23]
	v_mfma_f32_16x16x32_bf16 v[16:19], v[152:155], v[168:171], v[16:19]
	v_mfma_f32_16x16x32_bf16 v[12:15], v[144:147], v[176:179], v[12:15]
	v_mfma_f32_16x16x32_bf16 v[8:11], v[152:155], v[176:179], v[8:11]
	v_mfma_f32_16x16x32_bf16 v[4:7], v[144:147], v[184:187], v[4:7]
	v_mfma_f32_16x16x32_bf16 v[0:3], v[152:155], v[184:187], v[0:3]
	v_mfma_f32_16x16x32_bf16 v[28:31], v[148:151], v[164:167], v[28:31]
	v_mfma_f32_16x16x32_bf16 v[24:27], v[156:159], v[164:167], v[24:27]
	v_mfma_f32_16x16x32_bf16 v[20:23], v[148:151], v[172:175], v[20:23]
	v_mfma_f32_16x16x32_bf16 v[16:19], v[156:159], v[172:175], v[16:19]
	v_mfma_f32_16x16x32_bf16 v[12:15], v[148:151], v[180:183], v[12:15]
	v_mfma_f32_16x16x32_bf16 v[8:11], v[156:159], v[180:183], v[8:11]
	v_mfma_f32_16x16x32_bf16 v[4:7], v[148:151], v[188:191], v[4:7]
	v_mfma_f32_16x16x32_bf16 v[0:3], v[156:159], v[188:191], v[0:3]
	s_setprio 0
	s_barrier
	s_add_i32 s55, 0, 0x18000
	s_add_i32 s56, 0, 0x1c000
	v_add_u32_e32 v140, s55, v220
	v_add_u32_e32 v156, s56, v220
	ds_read_b128 v[128:131], v140
	ds_read_b128 v[132:135], v140 offset:1024
	ds_read_b128 v[136:139], v140 offset:2048
	ds_read_b128 v[140:143], v140 offset:3072
	ds_read_b128 v[144:147], v156
	ds_read_b128 v[148:151], v156 offset:1024
	ds_read_b128 v[152:155], v156 offset:2048
	ds_read_b128 v[156:159], v156 offset:3072
	s_add_u32 s22, s22, 0x4000
	s_addc_u32 s23, s23, 0
	s_mov_b32 m0, s27
	v_lshl_add_u64 v[192:193], s[22:23], 0, v[210:211]
	ds_read_b128 v[160:163], v223 offset:32768
	ds_read_b128 v[164:167], v223 offset:33792
	ds_read_b128 v[168:171], v223 offset:34816
	ds_read_b128 v[172:175], v223 offset:35840
	ds_read_b128 v[176:179], v223 offset:36864
	ds_read_b128 v[180:183], v223 offset:37888
	ds_read_b128 v[184:187], v223 offset:38912
	ds_read_b128 v[188:191], v223 offset:39936
	global_load_lds_dwordx4 v[192:193], off
	v_lshl_add_u64 v[192:193], s[22:23], 0, v[206:207]
	s_mov_b32 m0, s28
	s_nop 0
	global_load_lds_dwordx4 v[192:193], off
	s_waitcnt vmcnt(8)
	s_waitcnt lgkmcnt(0)
	s_barrier
	s_setprio 1
	s_waitcnt lgkmcnt(0)
	v_mfma_f32_16x16x32_bf16 v[124:127], v[128:131], v[160:163], v[124:127]
	v_mfma_f32_16x16x32_bf16 v[120:123], v[136:139], v[160:163], v[120:123]
	v_mfma_f32_16x16x32_bf16 v[116:119], v[128:131], v[168:171], v[116:119]
	v_mfma_f32_16x16x32_bf16 v[112:115], v[136:139], v[168:171], v[112:115]
	v_mfma_f32_16x16x32_bf16 v[108:111], v[128:131], v[176:179], v[108:111]
	v_mfma_f32_16x16x32_bf16 v[104:107], v[136:139], v[176:179], v[104:107]
	v_mfma_f32_16x16x32_bf16 v[100:103], v[128:131], v[184:187], v[100:103]
	v_mfma_f32_16x16x32_bf16 v[96:99], v[136:139], v[184:187], v[96:99]
	v_mfma_f32_16x16x32_bf16 v[124:127], v[132:135], v[164:167], v[124:127]
	v_mfma_f32_16x16x32_bf16 v[120:123], v[140:143], v[164:167], v[120:123]
	v_mfma_f32_16x16x32_bf16 v[116:119], v[132:135], v[172:175], v[116:119]
	v_mfma_f32_16x16x32_bf16 v[112:115], v[140:143], v[172:175], v[112:115]
	v_mfma_f32_16x16x32_bf16 v[108:111], v[132:135], v[180:183], v[108:111]
	v_mfma_f32_16x16x32_bf16 v[104:107], v[140:143], v[180:183], v[104:107]
	v_mfma_f32_16x16x32_bf16 v[100:103], v[132:135], v[188:191], v[100:103]
	v_mfma_f32_16x16x32_bf16 v[96:99], v[140:143], v[188:191], v[96:99]
	s_setprio 0
	s_setprio 1
	v_mfma_f32_16x16x32_bf16 v[68:71], v[144:147], v[160:163], v[68:71]
	v_mfma_f32_16x16x32_bf16 v[60:63], v[152:155], v[160:163], v[60:63]
	v_mfma_f32_16x16x32_bf16 v[52:55], v[144:147], v[168:171], v[52:55]
	v_mfma_f32_16x16x32_bf16 v[48:51], v[152:155], v[168:171], v[48:51]
	v_mfma_f32_16x16x32_bf16 v[44:47], v[144:147], v[176:179], v[44:47]
	v_mfma_f32_16x16x32_bf16 v[40:43], v[152:155], v[176:179], v[40:43]
	v_mfma_f32_16x16x32_bf16 v[36:39], v[144:147], v[184:187], v[36:39]
	v_mfma_f32_16x16x32_bf16 v[32:35], v[152:155], v[184:187], v[32:35]
	v_mfma_f32_16x16x32_bf16 v[68:71], v[148:151], v[164:167], v[68:71]
	v_mfma_f32_16x16x32_bf16 v[60:63], v[156:159], v[164:167], v[60:63]
	v_mfma_f32_16x16x32_bf16 v[52:55], v[148:151], v[172:175], v[52:55]
	v_mfma_f32_16x16x32_bf16 v[48:51], v[156:159], v[172:175], v[48:51]
	v_mfma_f32_16x16x32_bf16 v[44:47], v[148:151], v[180:183], v[44:47]
	v_mfma_f32_16x16x32_bf16 v[40:43], v[156:159], v[180:183], v[40:43]
	v_mfma_f32_16x16x32_bf16 v[36:39], v[148:151], v[188:191], v[36:39]
	v_mfma_f32_16x16x32_bf16 v[32:35], v[156:159], v[188:191], v[32:35]
	s_setprio 0
	s_barrier
; #define PG8_WAIT_V(n) asm volatile("s_waitcnt vmcnt(" #n ")" ::: "memory")
; template <class Epi, class Sched, bool ALIGN_EPI = false, bool SP2 = false>
; __device__ __forceinline__ void gemm_phase(PG8_LAS unsigned char* lds, const Gemm g, const Sched& S, const Epi& E, volatile PG8_LAS unsigned* sw = nullptr) {
;     ...
;             PG8_LDA(At, 1, 1); PG8_STAGE(PG8_SB(1, 0), b3, voffB); PG8_STAGE(PG8_SB(1, 1), b3 + hstep, voffB); PG8_STAGE(PG8_SA(1, 0), a3, voffA);
;             PG8_WAIT_V(8); PG8_WAIT_L(0); PG8_BAR; PG8_MMA(1, 0, At, B0); PG8_MMA(1, 1, At, B1); PG8_BAR; PG8_SCHED;
;             } else {
;             PG8_LDB(B0, 0, 0); PG8_SCHED; PG8_LDA(At, 0, 0); PG8_STAGE(PG8_SA(1, 1), a1 + hstep, voffA);
;             PG8_WAIT_L(8); PG8_BAR; PG8_WAIT_L(0); PG8_MMA(0, 0, At, B0); PG8_BAR; PG8_SCHED;
;             PG8_LDB(B1, 0, 1); PG8_STAGE(PG8_SB(0, 0), b2, voffB);
;             PG8_BAR; PG8_WAIT_L(0); PG8_MMA(0, 1, At, B1); PG8_BAR;
;             PG8_LDA(At, 0, 1); PG8_STAGE(PG8_SA(0, 0), a2, voffA);
;             PG8_BAR; PG8_WAIT_L(0); PG8_MMA(1, 0, At, B0); PG8_BAR; PG8_SCHED;
;             PG8_STAGE(PG8_SB(0, 1), b2 + hstep, voffB);
;             PG8_WAIT_V(6); PG8_BAR; PG8_MMA(1, 1, At, B1); PG8_BAR;
;             PG8_LDB(B0, 1, 0); PG8_SCHED; PG8_LDA(At, 1, 0); PG8_STAGE(PG8_SA(0, 1), a2 + hstep, voffA);
;             PG8_WAIT_L(8); PG8_BAR; PG8_WAIT_L(0); PG8_MMA(0, 0, At, B0); PG8_BAR; PG8_SCHED;
;             PG8_LDB(B1, 1, 1); PG8_STAGE(PG8_SB(1, 0), b3, voffB);
;             PG8_BAR; PG8_WAIT_L(0); PG8_MMA(0, 1, At, B1); PG8_BAR;
;             PG8_LDA(At, 1, 1); PG8_STAGE(PG8_SA(1, 0), a3, voffA);
;             PG8_BAR; PG8_WAIT_L(0); PG8_MMA(1, 0, At, B0); PG8_BAR; PG8_SCHED;
;             PG8_STAGE(PG8_SB(1, 1), b3 + hstep, voffB);
;             PG8_WAIT_V(6); PG8_BAR; PG8_MMA(1, 1, At, B1); PG8_BAR;
;             }
;         }
;         if constexpr (ALIGN_EPI) { if (wr == 0) PG8_BAR; }
;     __device__ __forceinline__ void operator()(AccRef acc, const pg8::Unit& u, int wr, int wc, int fr_, int fq_) const {
;         int fr = fr_, fq = fq_; asm volatile("" : "+v"(fr), "+v"(fq));
;         const int gpm = pm0 + u.pm, b = batch_of_tile(gpm), cl = wc * 32 + 8 * fq;
;         const char* xb = (const char*)(xg2 + ((size_t)(u.pm * 16 + u.pn * 4 + (wc >> 1)) << 14));
;         char* ob = (char*)(out + (size_t)gpm * 256 * D) + (size_t)u.pn * 1024;
	s_add_u32 s22, s20, 0x8000
	s_addc_u32 s23, s21, 0
	s_add_i32 s55, s55, s24
	v_lshl_add_u64 v[192:193], s[22:23], 0, v[208:209]
	s_mov_b32 m0, s55
	ds_read_b128 v[160:163], v223 offset:49152
	ds_read_b128 v[164:167], v223 offset:50176
	ds_read_b128 v[168:171], v223 offset:51200
	ds_read_b128 v[172:175], v223 offset:52224
	ds_read_b128 v[176:179], v223 offset:53248
	ds_read_b128 v[180:183], v223 offset:54272
	ds_read_b128 v[184:187], v223 offset:55296
	ds_read_b128 v[188:191], v223 offset:56320
	global_load_lds_dwordx4 v[192:193], off
	s_add_i32 m0, s55, 0x2000
	s_add_u32 s20, s20, 0xc000
	v_lshl_add_u64 v[192:193], s[22:23], 0, v[204:205]
	s_addc_u32 s21, s21, 0
	s_add_i32 s22, s56, s24
	global_load_lds_dwordx4 v[192:193], off
	v_lshl_add_u64 v[192:193], s[20:21], 0, v[208:209]
	s_mov_b32 m0, s22
	s_nop 0
	global_load_lds_dwordx4 v[192:193], off
	v_lshl_add_u64 v[192:193], s[20:21], 0, v[204:205]
	s_add_i32 m0, s22, 0x2000
	s_nop 0
	global_load_lds_dwordx4 v[192:193], off
	v_lshl_add_u64 v[192:193], s[18:19], 0, v[210:211]
	s_mov_b32 m0, s34
	s_nop 0
	global_load_lds_dwordx4 v[192:193], off
	v_lshl_add_u64 v[192:193], s[18:19], 0, v[206:207]
	s_mov_b32 m0, s35
	s_nop 0
	global_load_lds_dwordx4 v[192:193], off
	s_waitcnt vmcnt(8)
	s_waitcnt lgkmcnt(0)
	s_barrier
	s_setprio 1
	s_waitcnt lgkmcnt(0)
	v_mfma_f32_16x16x32_bf16 v[92:95], v[128:131], v[160:163], v[92:95]
	v_mfma_f32_16x16x32_bf16 v[88:91], v[136:139], v[160:163], v[88:91]
	v_mfma_f32_16x16x32_bf16 v[84:87], v[128:131], v[168:171], v[84:87]
	v_mfma_f32_16x16x32_bf16 v[80:83], v[136:139], v[168:171], v[80:83]
	v_mfma_f32_16x16x32_bf16 v[76:79], v[128:131], v[176:179], v[76:79]
	v_mfma_f32_16x16x32_bf16 v[72:75], v[136:139], v[176:179], v[72:75]
	v_mfma_f32_16x16x32_bf16 v[64:67], v[128:131], v[184:187], v[64:67]
	v_mfma_f32_16x16x32_bf16 v[56:59], v[136:139], v[184:187], v[56:59]
	v_mfma_f32_16x16x32_bf16 v[92:95], v[132:135], v[164:167], v[92:95]
	v_mfma_f32_16x16x32_bf16 v[88:91], v[140:143], v[164:167], v[88:91]
	v_mfma_f32_16x16x32_bf16 v[84:87], v[132:135], v[172:175], v[84:87]
	v_mfma_f32_16x16x32_bf16 v[80:83], v[140:143], v[172:175], v[80:83]
	v_mfma_f32_16x16x32_bf16 v[76:79], v[132:135], v[180:183], v[76:79]
	v_mfma_f32_16x16x32_bf16 v[72:75], v[140:143], v[180:183], v[72:75]
	v_mfma_f32_16x16x32_bf16 v[64:67], v[132:135], v[188:191], v[64:67]
	v_mfma_f32_16x16x32_bf16 v[56:59], v[140:143], v[188:191], v[56:59]
	s_setprio 0
	s_setprio 1
	v_mfma_f32_16x16x32_bf16 v[28:31], v[144:147], v[160:163], v[28:31]
	v_mfma_f32_16x16x32_bf16 v[24:27], v[152:155], v[160:163], v[24:27]
	v_mfma_f32_16x16x32_bf16 v[20:23], v[144:147], v[168:171], v[20:23]
	v_mfma_f32_16x16x32_bf16 v[16:19], v[152:155], v[168:171], v[16:19]
	v_mfma_f32_16x16x32_bf16 v[12:15], v[144:147], v[176:179], v[12:15]
	v_mfma_f32_16x16x32_bf16 v[8:11], v[152:155], v[176:179], v[8:11]
	v_mfma_f32_16x16x32_bf16 v[4:7], v[144:147], v[184:187], v[4:7]
	v_mfma_f32_16x16x32_bf16 v[0:3], v[152:155], v[184:187], v[0:3]
	v_mfma_f32_16x16x32_bf16 v[28:31], v[148:151], v[164:167], v[28:31]
	v_mfma_f32_16x16x32_bf16 v[24:27], v[156:159], v[164:167], v[24:27]
	v_mfma_f32_16x16x32_bf16 v[20:23], v[148:151], v[172:175], v[20:23]
	v_mfma_f32_16x16x32_bf16 v[16:19], v[156:159], v[172:175], v[16:19]
	v_mfma_f32_16x16x32_bf16 v[12:15], v[148:151], v[180:183], v[12:15]
	v_mfma_f32_16x16x32_bf16 v[8:11], v[156:159], v[180:183], v[8:11]
	v_mfma_f32_16x16x32_bf16 v[4:7], v[148:151], v[188:191], v[4:7]
	v_mfma_f32_16x16x32_bf16 v[0:3], v[156:159], v[188:191], v[0:3]
	s_setprio 0
	s_barrier
	s_add_i32 s54, s54, 2
	s_add_u32 s14, s14, 0x10000
	s_addc_u32 s15, s15, 0
	s_add_u32 s11, s11, 0x10000
	s_addc_u32 s13, s13, 0
	s_cmp_gt_u32 s54, 41
	s_cbranch_scc0 .LBB0_703
	s_and_b64 vcc, exec, s[4:5]
	s_cbranch_vccz .LBB0_706
	s_cmp_lg_u32 s98, 0
	s_cbranch_scc1 .LBB0_706
	s_barrier
.LBB0_706:
	s_add_i32 s14, s12, s70
	s_sub_i32 s11, s14, 64
	s_lshr_b32 s11, s11, 5
	s_add_i32 s22, s11, 8
	s_lshl_b32 s11, s12, 4
	s_lshl_b32 s12, s10, 2
	s_add_i32 s11, s11, s12
	s_or_b32 s12, s11, s38
	s_ashr_i32 s13, s12, 31
	s_lshl_b64 s[12:13], s[12:13], 15
	s_add_u32 s18, s71, s12
	s_addc_u32 s19, s72, s13
	s_ashr_i32 s15, s14, 31
	s_ashr_i32 s11, s10, 31
	s_lshl_b64 s[20:21], s[14:15], 20
	s_lshl_b64 s[12:13], s[10:11], 10
	s_lshr_b32 s11, s14, 3
	v_mov_b32_e32 v128, v218
	v_mov_b32_e32 v129, v219
	s_cmp_lt_i32 s14, 64
	s_cselect_b32 s11, s11, s22
	s_add_u32 s14, s58, s20
	v_lshlrev_b32_e32 v129, 3, v129
	v_add_u32_e32 v140, s36, v128
	s_addc_u32 s15, s59, s21
	s_lshl_b32 s11, s11, 10
	s_lshl_b32 s10, s10, 8
	v_add_u32_e32 v244, s37, v129
	v_add_u32_e32 v128, s39, v129
	v_lshlrev_b32_e32 v129, 7, v140
	s_add_i32 s11, s11, s10
	v_lshl_add_u32 v212, v128, 1, v129
	v_add_u32_e32 v128, s11, v244
	v_ashrrev_i32_e32 v129, 31, v128
	global_load_dwordx4 v[224:227], v212, s[18:19]
	v_lshlrev_b64 v[130:131], 2, v[128:129]
	v_lshl_add_u64 v[132:133], s[64:65], 0, v[130:131]
	global_load_dwordx4 v[188:191], v[132:133], off
	global_load_dwordx4 v[184:187], v[132:133], off offset:16
	v_lshl_add_u64 v[130:131], s[62:63], 0, v[130:131]
	global_load_dwordx4 v[180:183], v[130:131], off
	global_load_dwordx4 v[176:179], v[130:131], off offset:16
	global_load_dwordx4 v[228:231], v212, s[18:19] offset:2048
	v_lshl_add_u64 v[130:131], s[18:19], 0, v[212:213]
	v_add_co_u32_e32 v132, vcc, s31, v130
	v_add_u32_e32 v128, 0x80, v128
	s_nop 0
	v_addc_co_u32_e32 v133, vcc, 0, v131, vcc
	global_load_dwordx4 v[152:155], v[132:133], off offset:2048
	v_add_co_u32_e32 v132, vcc, s42, v130
	v_ashrrev_i32_e32 v129, 31, v128
	s_nop 0
	v_addc_co_u32_e32 v133, vcc, 0, v131, vcc
;     __device__ __forceinline__ void operator()(AccRef acc, const pg8::Unit& u, int wr, int wc, int fr_, int fq_) const {
;     ...
;         v4u xv[2][2][4];
; #pragma unroll
;         for (int bj = 0; bj < 2; ++bj)
; #pragma unroll
;             for (int ai = 0; ai < 2; ++ai)
; #pragma unroll
;                 for (int m = 0; m < 4; ++m) xv[bj][ai][m] = *(const v4u*)(xb + (size_t)((2 * bj) << 15) + (size_t)((ai * 128 + m * 16) * 128) + xgl);
;         f32x4 g2a[2][2], iGa[2][2];
; #pragma unroll
;         for (int bj = 0; bj < 2; ++bj)
; #pragma unroll
;             for (int n = 0; n < 2; ++n) { const int c_ = b * D + u.pn * 256 + bj * 128 + cl + 4 * n; g2a[bj][n] = *(const f32x4*)(g2t + c_); iGa[bj][n] = *(const f32x4*)(iG2t + c_); }
;         asm volatile("" ::: "memory");
;         const bool lastr = (u.pm & 8) != 0;
; #pragma unroll
;         for (int bj = 0; bj < 2; ++bj) {
; #pragma unroll
;             for (int ai = 0; ai < 2; ++ai)
; #pragma unroll
;                 for (int m = 0; m < 4; ++m) { char* orow = ob + (size_t)((ai * 128 + m * 16) * D + bj * 128) * 4; const v4u w = xv[bj][ai][m];
;                     const f32x4 x0 = (f32x4){bflo(w.x), bfhi(w.x), bflo(w.y), bfhi(w.y)} * iGa[bj][0], x1v = (f32x4){bflo(w.z), bfhi(w.z), bflo(w.w), bfhi(w.w)} * iGa[bj][1];
;                     const f32x4 o0 = x0 + g2a[bj][0] * acc[ai][bj][m][0], o1 = x1v + g2a[bj][1] * acc[ai][bj][m][1];
;                     if (lastr) { __builtin_nontemporal_store(o0, (f32x4*)(orow + loff)); __builtin_nontemporal_store(o1, (f32x4*)(orow + 16 + loff)); }
;                     else { *(f32x4*)(orow + loff) = o0; *(f32x4*)(orow + 16 + loff) = o1; } }
	global_load_dwordx4 v[232:235], v[132:133], off
	global_load_dwordx4 v[236:239], v[132:133], off offset:2048
	v_add_co_u32_e32 v132, vcc, s33, v130
	v_lshlrev_b64 v[128:129], 2, v[128:129]
	s_nop 0
	v_addc_co_u32_e32 v133, vcc, 0, v131, vcc
	v_add_co_u32_e32 v134, vcc, s43, v130
	v_lshl_add_u64 v[144:145], s[64:65], 0, v[128:129]
	s_nop 0
	v_addc_co_u32_e32 v135, vcc, 0, v131, vcc
	global_load_dwordx4 v[240:243], v[134:135], off offset:-4096
	global_load_dwordx4 v[196:199], v[134:135], off
	global_load_dwordx4 v[192:195], v[134:135], off offset:2048
	v_add_co_u32_e32 v134, vcc, s30, v130
	v_lshlrev_b32_e32 v212, 12, v140
	s_nop 0
	v_addc_co_u32_e32 v135, vcc, 0, v131, vcc
	v_add_co_u32_e32 v136, vcc, s44, v130
	v_lshl_add_u32 v212, v244, 2, v212
	s_nop 0
	v_addc_co_u32_e32 v137, vcc, 0, v131, vcc
	global_load_dwordx4 v[200:203], v[132:133], off offset:2048
	global_load_dwordx4 v[168:171], v[134:135], off offset:2048
	global_load_dwordx4 v[172:175], v[136:137], off offset:-4096
	global_load_dwordx4 v[164:167], v[136:137], off
	v_add_co_u32_e32 v130, vcc, s45, v130
	s_add_u32 s10, s14, s12
	s_nop 0
	v_addc_co_u32_e32 v131, vcc, 0, v131, vcc
	global_load_dwordx4 v[160:163], v[136:137], off offset:2048
	global_load_dwordx4 v[156:159], v[130:131], off offset:-4096
	global_load_dwordx4 v[148:151], v[130:131], off
	s_nop 0
	global_load_dwordx4 v[136:139], v[130:131], off offset:2048
	v_lshl_add_u64 v[130:131], s[62:63], 0, v[128:129]
	global_load_dwordx4 v[132:135], v[130:131], off
	global_load_dwordx4 v[140:143], v[144:145], off offset:16
	s_nop 0
	global_load_dwordx4 v[128:131], v[130:131], off offset:16
	s_nop 0
	global_load_dwordx4 v[144:147], v[144:145], off
	s_addc_u32 s11, s15, s13
	s_waitcnt vmcnt(0)
	v_lshlrev_b32_e32 v244, 16, v224
	v_and_b32_e32 v245, 0xffff0000, v224
	v_lshlrev_b32_e32 v224, 16, v225
	v_and_b32_e32 v225, 0xffff0000, v225
	v_pk_mul_f32 v[244:245], v[188:189], v[244:245]
	v_pk_mul_f32 v[224:225], v[190:191], v[224:225]
	v_lshlrev_b32_e32 v246, 16, v226
	v_and_b32_e32 v247, 0xffff0000, v226
	v_lshlrev_b32_e32 v226, 16, v227
	v_and_b32_e32 v227, 0xffff0000, v227
	v_pk_mul_f32 v[246:247], v[184:185], v[246:247]
	v_pk_mul_f32 v[226:227], v[186:187], v[226:227]
	v_pk_fma_f32 v[126:127], v[126:127], v[182:183], v[224:225]
	v_pk_fma_f32 v[124:125], v[124:125], v[180:181], v[244:245]
	v_pk_fma_f32 v[226:227], v[122:123], v[178:179], v[226:227]
	v_pk_fma_f32 v[224:225], v[120:121], v[176:177], v[246:247]
	global_store_dwordx4 v212, v[124:127], s[10:11]
	global_store_dwordx4 v212, v[224:227], s[10:11] offset:16
	v_lshlrev_b32_e32 v122, 16, v228
	v_and_b32_e32 v123, 0xffff0000, v228
	v_lshlrev_b32_e32 v126, 16, v230
	v_and_b32_e32 v127, 0xffff0000, v230
	v_lshl_add_u64 v[120:121], s[10:11], 0, v[212:213]
	v_lshlrev_b32_e32 v124, 16, v229
	v_and_b32_e32 v125, 0xffff0000, v229
	v_pk_mul_f32 v[122:123], v[188:189], v[122:123]
	v_pk_mul_f32 v[126:127], v[184:185], v[126:127]
	v_pk_mul_f32 v[124:125], v[190:191], v[124:125]
	v_lshlrev_b32_e32 v224, 16, v231
	v_and_b32_e32 v225, 0xffff0000, v231
	v_pk_fma_f32 v[116:117], v[116:117], v[180:181], v[122:123]
	v_pk_fma_f32 v[122:123], v[112:113], v[176:177], v[126:127]
	v_add_co_u32_e32 v112, vcc, s30, v120
	v_pk_mul_f32 v[224:225], v[186:187], v[224:225]
	v_pk_fma_f32 v[118:119], v[118:119], v[182:183], v[124:125]
	v_addc_co_u32_e32 v113, vcc, 0, v121, vcc
	v_pk_fma_f32 v[124:125], v[114:115], v[178:179], v[224:225]
	global_store_dwordx4 v[112:113], v[116:119], off
	global_store_dwordx4 v[112:113], v[122:125], off offset:16
	v_lshlrev_b32_e32 v114, 16, v232
	v_and_b32_e32 v115, 0xffff0000, v232
	v_lshlrev_b32_e32 v118, 16, v234
	v_and_b32_e32 v119, 0xffff0000, v234
	v_lshlrev_b32_e32 v116, 16, v233
	v_and_b32_e32 v117, 0xffff0000, v233
	v_pk_mul_f32 v[114:115], v[188:189], v[114:115]
	v_pk_mul_f32 v[118:119], v[184:185], v[118:119]
	v_pk_mul_f32 v[116:117], v[190:191], v[116:117]
	v_lshlrev_b32_e32 v122, 16, v235
	v_and_b32_e32 v123, 0xffff0000, v235
	v_pk_fma_f32 v[108:109], v[108:109], v[180:181], v[114:115]
	v_pk_fma_f32 v[114:115], v[104:105], v[176:177], v[118:119]
	v_add_co_u32_e32 v104, vcc, s46, v120
	v_pk_mul_f32 v[122:123], v[186:187], v[122:123]
	v_pk_fma_f32 v[110:111], v[110:111], v[182:183], v[116:117]
	v_addc_co_u32_e32 v105, vcc, 0, v121, vcc
	v_pk_fma_f32 v[116:117], v[106:107], v[178:179], v[122:123]
	global_store_dwordx4 v[104:105], v[108:111], off
	global_store_dwordx4 v[104:105], v[114:117], off offset:16
	v_lshlrev_b32_e32 v106, 16, v236
	v_and_b32_e32 v107, 0xffff0000, v236
	v_lshlrev_b32_e32 v110, 16, v238
	v_and_b32_e32 v111, 0xffff0000, v238
	v_lshlrev_b32_e32 v108, 16, v237
	v_and_b32_e32 v109, 0xffff0000, v237
	v_pk_mul_f32 v[106:107], v[188:189], v[106:107]
	v_pk_mul_f32 v[110:111], v[184:185], v[110:111]
	v_pk_mul_f32 v[108:109], v[190:191], v[108:109]
	v_lshlrev_b32_e32 v114, 16, v239
	v_and_b32_e32 v115, 0xffff0000, v239
	v_pk_fma_f32 v[100:101], v[100:101], v[180:181], v[106:107]
	v_pk_fma_f32 v[106:107], v[96:97], v[176:177], v[110:111]
	v_add_co_u32_e32 v96, vcc, s47, v120
	v_pk_mul_f32 v[114:115], v[186:187], v[114:115]
	v_pk_fma_f32 v[102:103], v[102:103], v[182:183], v[108:109]
	v_addc_co_u32_e32 v97, vcc, 0, v121, vcc
	v_pk_fma_f32 v[108:109], v[98:99], v[178:179], v[114:115]
	global_store_dwordx4 v[96:97], v[100:103], off
	global_store_dwordx4 v[96:97], v[106:109], off offset:16
	v_lshlrev_b32_e32 v98, 16, v240
	v_and_b32_e32 v99, 0xffff0000, v240
	v_lshlrev_b32_e32 v102, 16, v242
	v_and_b32_e32 v103, 0xffff0000, v242
	v_lshlrev_b32_e32 v100, 16, v241
	v_and_b32_e32 v101, 0xffff0000, v241
	v_pk_mul_f32 v[98:99], v[188:189], v[98:99]
;     __device__ __forceinline__ void operator()(AccRef acc, const pg8::Unit& u, int wr, int wc, int fr_, int fq_) const {
;     ...
;         for (int bj = 0; bj < 2; ++bj) {
; #pragma unroll
;             for (int ai = 0; ai < 2; ++ai)
; #pragma unroll
;                 for (int m = 0; m < 4; ++m) { char* orow = ob + (size_t)((ai * 128 + m * 16) * D + bj * 128) * 4; const v4u w = xv[bj][ai][m];
;                     const f32x4 x0 = (f32x4){bflo(w.x), bfhi(w.x), bflo(w.y), bfhi(w.y)} * iGa[bj][0], x1v = (f32x4){bflo(w.z), bfhi(w.z), bflo(w.w), bfhi(w.w)} * iGa[bj][1];
;                     const f32x4 o0 = x0 + g2a[bj][0] * acc[ai][bj][m][0], o1 = x1v + g2a[bj][1] * acc[ai][bj][m][1];
;                     if (lastr) { __builtin_nontemporal_store(o0, (f32x4*)(orow + loff)); __builtin_nontemporal_store(o1, (f32x4*)(orow + 16 + loff)); }
;                     else { *(f32x4*)(orow + loff) = o0; *(f32x4*)(orow + 16 + loff) = o1; } }
	v_pk_mul_f32 v[102:103], v[184:185], v[102:103]
	v_pk_mul_f32 v[100:101], v[190:191], v[100:101]
	v_lshlrev_b32_e32 v106, 16, v243
	v_and_b32_e32 v107, 0xffff0000, v243
	v_pk_fma_f32 v[92:93], v[92:93], v[180:181], v[98:99]
	v_pk_fma_f32 v[98:99], v[88:89], v[176:177], v[102:103]
	v_add_co_u32_e32 v88, vcc, s48, v120
	v_pk_mul_f32 v[106:107], v[186:187], v[106:107]
	v_pk_fma_f32 v[94:95], v[94:95], v[182:183], v[100:101]
	v_addc_co_u32_e32 v89, vcc, 0, v121, vcc
	v_pk_fma_f32 v[100:101], v[90:91], v[178:179], v[106:107]
	global_store_dwordx4 v[88:89], v[92:95], off
	global_store_dwordx4 v[88:89], v[98:101], off offset:16
	v_lshlrev_b32_e32 v90, 16, v200
	v_and_b32_e32 v91, 0xffff0000, v200
	v_lshlrev_b32_e32 v94, 16, v202
	v_and_b32_e32 v95, 0xffff0000, v202
	v_lshlrev_b32_e32 v92, 16, v201
	v_and_b32_e32 v93, 0xffff0000, v201
	v_pk_mul_f32 v[90:91], v[188:189], v[90:91]
	v_pk_mul_f32 v[94:95], v[184:185], v[94:95]
	v_pk_mul_f32 v[92:93], v[190:191], v[92:93]
	v_lshlrev_b32_e32 v98, 16, v203
	v_and_b32_e32 v99, 0xffff0000, v203
	v_pk_fma_f32 v[84:85], v[84:85], v[180:181], v[90:91]
	v_pk_fma_f32 v[90:91], v[80:81], v[176:177], v[94:95]
	v_add_co_u32_e32 v80, vcc, s49, v120
	v_pk_mul_f32 v[98:99], v[186:187], v[98:99]
	v_pk_fma_f32 v[86:87], v[86:87], v[182:183], v[92:93]
	v_addc_co_u32_e32 v81, vcc, 0, v121, vcc
	v_pk_fma_f32 v[92:93], v[82:83], v[178:179], v[98:99]
	global_store_dwordx4 v[80:81], v[84:87], off
	global_store_dwordx4 v[80:81], v[90:93], off offset:16
	v_lshlrev_b32_e32 v82, 16, v196
	v_and_b32_e32 v83, 0xffff0000, v196
	v_lshlrev_b32_e32 v86, 16, v198
	v_and_b32_e32 v87, 0xffff0000, v198
	v_lshlrev_b32_e32 v84, 16, v197
	v_and_b32_e32 v85, 0xffff0000, v197
	v_pk_mul_f32 v[82:83], v[188:189], v[82:83]
	v_pk_mul_f32 v[86:87], v[184:185], v[86:87]
	v_pk_mul_f32 v[84:85], v[190:191], v[84:85]
	v_lshlrev_b32_e32 v90, 16, v199
	v_and_b32_e32 v91, 0xffff0000, v199
	v_pk_fma_f32 v[76:77], v[76:77], v[180:181], v[82:83]
	v_pk_fma_f32 v[82:83], v[72:73], v[176:177], v[86:87]
	v_add_co_u32_e32 v72, vcc, s50, v120
	v_pk_mul_f32 v[90:91], v[186:187], v[90:91]
	v_pk_fma_f32 v[78:79], v[78:79], v[182:183], v[84:85]
	v_addc_co_u32_e32 v73, vcc, 0, v121, vcc
	v_pk_fma_f32 v[84:85], v[74:75], v[178:179], v[90:91]
	global_store_dwordx4 v[72:73], v[76:79], off
	global_store_dwordx4 v[72:73], v[82:85], off offset:16
	v_lshlrev_b32_e32 v74, 16, v192
	v_and_b32_e32 v75, 0xffff0000, v192
	v_lshlrev_b32_e32 v78, 16, v194
	v_and_b32_e32 v79, 0xffff0000, v194
	v_lshlrev_b32_e32 v76, 16, v193
	v_and_b32_e32 v77, 0xffff0000, v193
	v_pk_mul_f32 v[74:75], v[188:189], v[74:75]
	v_pk_mul_f32 v[78:79], v[184:185], v[78:79]
	v_pk_mul_f32 v[76:77], v[190:191], v[76:77]
	v_lshlrev_b32_e32 v82, 16, v195
	v_and_b32_e32 v83, 0xffff0000, v195
	v_pk_fma_f32 v[64:65], v[64:65], v[180:181], v[74:75]
	v_pk_fma_f32 v[74:75], v[56:57], v[176:177], v[78:79]
	v_add_co_u32_e32 v56, vcc, s51, v120
	v_pk_mul_f32 v[82:83], v[186:187], v[82:83]
	v_pk_fma_f32 v[66:67], v[66:67], v[182:183], v[76:77]
	v_addc_co_u32_e32 v57, vcc, 0, v121, vcc
	v_pk_fma_f32 v[76:77], v[58:59], v[178:179], v[82:83]
	global_store_dwordx4 v[56:57], v[64:67], off
	global_store_dwordx4 v[56:57], v[74:77], off offset:16
	v_lshlrev_b32_e32 v58, 16, v172
	v_and_b32_e32 v59, 0xffff0000, v172
	v_lshlrev_b32_e32 v64, 16, v173
	v_and_b32_e32 v65, 0xffff0000, v173
	v_lshlrev_b32_e32 v66, 16, v174
	v_and_b32_e32 v67, 0xffff0000, v174
	v_lshlrev_b32_e32 v74, 16, v175
	v_and_b32_e32 v75, 0xffff0000, v175
	v_pk_mul_f32 v[64:65], v[146:147], v[64:65]
	v_pk_mul_f32 v[58:59], v[144:145], v[58:59]
	v_pk_mul_f32 v[74:75], v[142:143], v[74:75]
	v_pk_mul_f32 v[76:77], v[140:141], v[66:67]
	v_pk_fma_f32 v[66:67], v[70:71], v[134:135], v[64:65]
	v_pk_fma_f32 v[64:65], v[68:69], v[132:133], v[58:59]
	v_pk_fma_f32 v[62:63], v[62:63], v[130:131], v[74:75]
	v_pk_fma_f32 v[60:61], v[60:61], v[128:129], v[76:77]
	global_store_dwordx4 v212, v[64:67], s[10:11] offset:512
	global_store_dwordx4 v212, v[60:63], s[10:11] offset:528
	v_lshlrev_b32_e32 v58, 16, v168
	v_and_b32_e32 v59, 0xffff0000, v168
	v_lshlrev_b32_e32 v60, 16, v169
	v_and_b32_e32 v61, 0xffff0000, v169
	v_lshlrev_b32_e32 v62, 16, v170
	v_and_b32_e32 v63, 0xffff0000, v170
	v_lshlrev_b32_e32 v64, 16, v171
	v_and_b32_e32 v65, 0xffff0000, v171
	v_pk_mul_f32 v[60:61], v[146:147], v[60:61]
	v_pk_mul_f32 v[58:59], v[144:145], v[58:59]
	v_pk_mul_f32 v[64:65], v[142:143], v[64:65]
	v_pk_mul_f32 v[62:63], v[140:141], v[62:63]
	v_pk_fma_f32 v[54:55], v[54:55], v[134:135], v[60:61]
	v_pk_fma_f32 v[52:53], v[52:53], v[132:133], v[58:59]
	v_pk_fma_f32 v[50:51], v[50:51], v[130:131], v[64:65]
	v_pk_fma_f32 v[48:49], v[48:49], v[128:129], v[62:63]
	global_store_dwordx4 v[112:113], v[52:55], off offset:512
	global_store_dwordx4 v[112:113], v[48:51], off offset:528
	s_and_b64 vcc, exec, s[0:1]
	v_lshlrev_b32_e32 v52, 16, v166
; #define PG8_BAR __builtin_amdgcn_s_barrier()
; template <class Epi, class Sched, bool ALIGN_EPI = false, bool SP2 = false>
; __device__ __forceinline__ void gemm_phase(PG8_LAS unsigned char* lds, const Gemm g, const Sched& S, const Epi& E, volatile PG8_LAS unsigned* sw = nullptr) {
;     ...
;         if (!has_next) break;
; #pragma unroll
;         for (int a = 0; a < 2; ++a)
; #pragma unroll
;             for (int b = 0; b < 2; ++b)
; #pragma unroll
;                 for (int m = 0; m < 4; ++m)
; #pragma unroll
;                     for (int n = 0; n < 2; ++n) acc[a][b][m][n] = (f32x4){0.f, 0.f, 0.f, 0.f};
;         cur = nxt; cA = nA; cB = nB; ++ui;
;         if constexpr (ALIGN_EPI) { if (wr == 1) PG8_BAR; }
;     __device__ __forceinline__ void operator()(AccRef acc, const pg8::Unit& u, int wr, int wc, int fr_, int fq_) const {
;     ...
;         for (int bj = 0; bj < 2; ++bj) {
; #pragma unroll
;             for (int ai = 0; ai < 2; ++ai)
; #pragma unroll
;                 for (int m = 0; m < 4; ++m) { char* orow = ob + (size_t)((ai * 128 + m * 16) * D + bj * 128) * 4; const v4u w = xv[bj][ai][m];
;                     const f32x4 x0 = (f32x4){bflo(w.x), bfhi(w.x), bflo(w.y), bfhi(w.y)} * iGa[bj][0], x1v = (f32x4){bflo(w.z), bfhi(w.z), bflo(w.w), bfhi(w.w)} * iGa[bj][1];
;                     const f32x4 o0 = x0 + g2a[bj][0] * acc[ai][bj][m][0], o1 = x1v + g2a[bj][1] * acc[ai][bj][m][1];
;                     if (lastr) { __builtin_nontemporal_store(o0, (f32x4*)(orow + loff)); __builtin_nontemporal_store(o1, (f32x4*)(orow + 16 + loff)); }
;                     else { *(f32x4*)(orow + loff) = o0; *(f32x4*)(orow + 16 + loff) = o1; } }
	v_lshlrev_b32_e32 v48, 16, v164
	v_and_b32_e32 v49, 0xffff0000, v164
	v_lshlrev_b32_e32 v50, 16, v165
	v_and_b32_e32 v51, 0xffff0000, v165
	v_and_b32_e32 v53, 0xffff0000, v166
	v_lshlrev_b32_e32 v54, 16, v167
	v_and_b32_e32 v55, 0xffff0000, v167
	v_pk_mul_f32 v[50:51], v[146:147], v[50:51]
	v_pk_mul_f32 v[48:49], v[144:145], v[48:49]
	v_pk_mul_f32 v[54:55], v[142:143], v[54:55]
	v_pk_mul_f32 v[52:53], v[140:141], v[52:53]
	v_pk_fma_f32 v[46:47], v[46:47], v[134:135], v[50:51]
	v_pk_fma_f32 v[44:45], v[44:45], v[132:133], v[48:49]
	v_pk_fma_f32 v[42:43], v[42:43], v[130:131], v[54:55]
	v_pk_fma_f32 v[40:41], v[40:41], v[128:129], v[52:53]
	global_store_dwordx4 v[104:105], v[44:47], off offset:512
	global_store_dwordx4 v[104:105], v[40:43], off offset:528
	s_mov_b64 s[0:1], -1
	v_lshlrev_b32_e32 v44, 16, v162
	v_lshlrev_b32_e32 v40, 16, v160
	v_and_b32_e32 v41, 0xffff0000, v160
	v_lshlrev_b32_e32 v42, 16, v161
	v_and_b32_e32 v43, 0xffff0000, v161
	v_and_b32_e32 v45, 0xffff0000, v162
	v_lshlrev_b32_e32 v46, 16, v163
	v_and_b32_e32 v47, 0xffff0000, v163
	v_pk_mul_f32 v[42:43], v[146:147], v[42:43]
	v_pk_mul_f32 v[40:41], v[144:145], v[40:41]
	v_pk_mul_f32 v[46:47], v[142:143], v[46:47]
	v_pk_mul_f32 v[44:45], v[140:141], v[44:45]
	v_pk_fma_f32 v[38:39], v[38:39], v[134:135], v[42:43]
	v_pk_fma_f32 v[36:37], v[36:37], v[132:133], v[40:41]
	v_pk_fma_f32 v[34:35], v[34:35], v[130:131], v[46:47]
	v_pk_fma_f32 v[32:33], v[32:33], v[128:129], v[44:45]
	global_store_dwordx4 v[96:97], v[36:39], off offset:512
	global_store_dwordx4 v[96:97], v[32:35], off offset:528
	s_nop 0
	v_lshlrev_b32_e32 v36, 16, v158
	v_lshlrev_b32_e32 v32, 16, v156
	v_and_b32_e32 v33, 0xffff0000, v156
	v_lshlrev_b32_e32 v34, 16, v157
	v_and_b32_e32 v35, 0xffff0000, v157
	v_and_b32_e32 v37, 0xffff0000, v158
	v_lshlrev_b32_e32 v38, 16, v159
	v_and_b32_e32 v39, 0xffff0000, v159
	v_pk_mul_f32 v[34:35], v[146:147], v[34:35]
	v_pk_mul_f32 v[32:33], v[144:145], v[32:33]
	v_pk_mul_f32 v[38:39], v[142:143], v[38:39]
	v_pk_mul_f32 v[36:37], v[140:141], v[36:37]
	v_pk_fma_f32 v[30:31], v[30:31], v[134:135], v[34:35]
	v_pk_fma_f32 v[28:29], v[28:29], v[132:133], v[32:33]
	v_pk_fma_f32 v[26:27], v[26:27], v[130:131], v[38:39]
	v_pk_fma_f32 v[24:25], v[24:25], v[128:129], v[36:37]
	global_store_dwordx4 v[88:89], v[28:31], off offset:512
	global_store_dwordx4 v[88:89], v[24:27], off offset:528
	s_nop 0
	v_lshlrev_b32_e32 v28, 16, v154
	v_lshlrev_b32_e32 v24, 16, v152
	v_and_b32_e32 v25, 0xffff0000, v152
	v_lshlrev_b32_e32 v26, 16, v153
	v_and_b32_e32 v27, 0xffff0000, v153
	v_and_b32_e32 v29, 0xffff0000, v154
	v_lshlrev_b32_e32 v30, 16, v155
	v_and_b32_e32 v31, 0xffff0000, v155
	v_pk_mul_f32 v[26:27], v[146:147], v[26:27]
	v_pk_mul_f32 v[24:25], v[144:145], v[24:25]
	v_pk_mul_f32 v[30:31], v[142:143], v[30:31]
	v_pk_mul_f32 v[28:29], v[140:141], v[28:29]
	v_pk_fma_f32 v[22:23], v[22:23], v[134:135], v[26:27]
	v_pk_fma_f32 v[20:21], v[20:21], v[132:133], v[24:25]
	v_pk_fma_f32 v[18:19], v[18:19], v[130:131], v[30:31]
	v_pk_fma_f32 v[16:17], v[16:17], v[128:129], v[28:29]
	global_store_dwordx4 v[80:81], v[20:23], off offset:512
	global_store_dwordx4 v[80:81], v[16:19], off offset:528
	s_nop 0
	v_lshlrev_b32_e32 v20, 16, v150
	v_lshlrev_b32_e32 v16, 16, v148
	v_and_b32_e32 v17, 0xffff0000, v148
	v_lshlrev_b32_e32 v18, 16, v149
	v_and_b32_e32 v19, 0xffff0000, v149
	v_and_b32_e32 v21, 0xffff0000, v150
	v_lshlrev_b32_e32 v22, 16, v151
	v_and_b32_e32 v23, 0xffff0000, v151
	v_pk_mul_f32 v[18:19], v[146:147], v[18:19]
	v_pk_mul_f32 v[16:17], v[144:145], v[16:17]
	v_pk_mul_f32 v[22:23], v[142:143], v[22:23]
	v_pk_mul_f32 v[20:21], v[140:141], v[20:21]
	v_pk_fma_f32 v[14:15], v[14:15], v[134:135], v[18:19]
	v_pk_fma_f32 v[12:13], v[12:13], v[132:133], v[16:17]
	v_pk_fma_f32 v[10:11], v[10:11], v[130:131], v[22:23]
	v_pk_fma_f32 v[8:9], v[8:9], v[128:129], v[20:21]
	global_store_dwordx4 v[72:73], v[12:15], off offset:512
	global_store_dwordx4 v[72:73], v[8:11], off offset:528
	s_nop 0
	v_lshlrev_b32_e32 v12, 16, v138
	v_lshlrev_b32_e32 v8, 16, v136
	v_and_b32_e32 v9, 0xffff0000, v136
	v_lshlrev_b32_e32 v10, 16, v137
	v_and_b32_e32 v11, 0xffff0000, v137
	v_pk_mul_f32 v[10:11], v[146:147], v[10:11]
	v_pk_mul_f32 v[8:9], v[144:145], v[8:9]
	v_and_b32_e32 v13, 0xffff0000, v138
	v_lshlrev_b32_e32 v14, 16, v139
	v_and_b32_e32 v15, 0xffff0000, v139
	v_pk_mul_f32 v[14:15], v[142:143], v[14:15]
	v_pk_mul_f32 v[12:13], v[140:141], v[12:13]
	v_pk_fma_f32 v[6:7], v[6:7], v[134:135], v[10:11]
	v_pk_fma_f32 v[4:5], v[4:5], v[132:133], v[8:9]
	v_pk_fma_f32 v[2:3], v[2:3], v[130:131], v[14:15]
	v_pk_fma_f32 v[0:1], v[0:1], v[128:129], v[12:13]
	global_store_dwordx4 v[56:57], v[4:7], off offset:512
	global_store_dwordx4 v[56:57], v[0:3], off offset:528
	s_cbranch_vccnz .LBB0_695
	s_andn2_b64 vcc, exec, s[2:3]
	s_cbranch_vccnz .LBB0_694
	s_branch .LBB0_694
